# SGU: bias loads batched + final-stage uA/gA loads hoisted with counted vmcnt (on top of attention interleave)
# baseline (speedup 1.0000x reference)
; __device__ __forceinline__ int crow(int r, int hi) { return (r & 3) + 8 * (r >> 2) + 4 * hi; }
; __device__ __forceinline__ unsigned pk2(float lo, float hi) { return pg8::cvt_pk_bf16(lo, hi); }
; __device__ __forceinline__ void sgu_unit(const Args& a, int l, int unit, unsigned char* ldsg) {
;     ...
; #pragma unroll
;         for (int r = 0; r < 16; ++r) { const int i = iw * 32 + att::crow(r, hi); const float bias = a.in[7][(l * 8 + g) * 128 + i];
; #pragma unroll
;             for (int d0 = 0; d0 < 4; ++d0) *(bf16r*)(lds + OT_OFF + i * OT_PITCH + (eh * 128 + d0 * 32 + r32) * 2) = (bf16r)(pk2(o[d0][r] + bias, 0.f) & 0xffffu); }
.LBB0_320:
	v_lshl_add_u64 v[64:65], v[156:157], 0, s[24:25]
	v_lshl_add_u64 v[242:243], v[156:157], 0, s[24:25]
	global_load_dword v226, v[242:243], off
	global_load_dword v227, v[242:243], off offset:4
	global_load_dword v228, v[242:243], off offset:8
	global_load_dword v229, v[242:243], off offset:12
	global_load_dword v230, v[242:243], off offset:32
	global_load_dword v231, v[242:243], off offset:36
	global_load_dword v232, v[242:243], off offset:40
	global_load_dword v233, v[242:243], off offset:44
	global_load_dword v234, v[242:243], off offset:64
	global_load_dword v235, v[242:243], off offset:68
	global_load_dword v236, v[242:243], off offset:72
	global_load_dword v237, v[242:243], off offset:76
	global_load_dword v238, v[242:243], off offset:96
	global_load_dword v239, v[242:243], off offset:100
	global_load_dword v240, v[242:243], off offset:104
	global_load_dword v241, v[242:243], off offset:108
	s_waitcnt vmcnt(0)
	v_mov_b32_e32 v66, v226
	v_add_u32_e32 v67, v177, v176
	v_lshl_add_u64 v[154:155], v[154:155], 0, s[22:23]
	s_waitcnt vmcnt(0)
	v_add_f32_e32 v0, v0, v66
	v_cvt_pk_bf16_f32 v0, v0, v113
	v_add_f32_e32 v16, v16, v66
	ds_write_b16 v67, v0
	v_cvt_pk_bf16_f32 v0, v16, v113
	v_add_f32_e32 v32, v32, v66
	ds_write_b16 v67, v0 offset:64
	v_cvt_pk_bf16_f32 v0, v32, v113
	s_nop 0
	v_add_f32_e32 v48, v48, v66
	ds_write_b16 v67, v0 offset:128
	v_cvt_pk_bf16_f32 v0, v48, v113
	v_mov_b32_e32 v16, v227
	ds_write_b16 v67, v0 offset:192
	s_waitcnt vmcnt(0)
	v_add_f32_e32 v0, v1, v16
	v_cvt_pk_bf16_f32 v0, v0, v113
	v_add_f32_e32 v1, v17, v16
	ds_write_b16 v180, v0
	v_cvt_pk_bf16_f32 v0, v1, v113
	v_add_f32_e32 v17, v33, v16
	ds_write_b16 v180, v0 offset:64
	v_cvt_pk_bf16_f32 v0, v17, v113
	v_add_f32_e32 v16, v49, v16
	ds_write_b16 v180, v0 offset:128
	v_cvt_pk_bf16_f32 v0, v16, v113
	v_mov_b32_e32 v1, v228
	ds_write_b16 v180, v0 offset:192
	s_waitcnt vmcnt(0)
	v_add_f32_e32 v0, v2, v1
	v_cvt_pk_bf16_f32 v0, v0, v113
	v_add_f32_e32 v2, v18, v1
	ds_write_b16 v181, v0
	v_cvt_pk_bf16_f32 v0, v2, v113
	v_add_f32_e32 v16, v34, v1
	v_add_f32_e32 v1, v50, v1
	ds_write_b16 v181, v0 offset:64
	v_cvt_pk_bf16_f32 v0, v16, v113
	ds_write_b16 v181, v0 offset:128
	v_cvt_pk_bf16_f32 v0, v1, v113
	v_mov_b32_e32 v1, v229
	ds_write_b16 v181, v0 offset:192
	s_waitcnt vmcnt(0)
	v_add_f32_e32 v0, v3, v1
	v_cvt_pk_bf16_f32 v0, v0, v113
	v_add_f32_e32 v2, v19, v1
	ds_write_b16 v182, v0
	v_cvt_pk_bf16_f32 v0, v2, v113
	v_add_f32_e32 v3, v35, v1
	v_add_f32_e32 v1, v51, v1
	ds_write_b16 v182, v0 offset:64
	v_cvt_pk_bf16_f32 v0, v3, v113
	ds_write_b16 v182, v0 offset:128
	v_cvt_pk_bf16_f32 v0, v1, v113
	v_mov_b32_e32 v1, v230
	ds_write_b16 v182, v0 offset:192
	s_waitcnt vmcnt(0)
	v_add_f32_e32 v0, v4, v1
	v_cvt_pk_bf16_f32 v0, v0, v113
	v_add_f32_e32 v2, v20, v1
	ds_write_b16 v183, v0
	v_cvt_pk_bf16_f32 v0, v2, v113
	v_add_f32_e32 v3, v36, v1
	v_add_f32_e32 v1, v52, v1
	ds_write_b16 v183, v0 offset:64
	v_cvt_pk_bf16_f32 v0, v3, v113
	ds_write_b16 v183, v0 offset:128
	v_cvt_pk_bf16_f32 v0, v1, v113
	v_mov_b32_e32 v1, v231
	ds_write_b16 v183, v0 offset:192
	s_waitcnt vmcnt(0)
	v_add_f32_e32 v0, v5, v1
	v_cvt_pk_bf16_f32 v0, v0, v113
	v_add_f32_e32 v2, v21, v1
	ds_write_b16 v184, v0
	v_cvt_pk_bf16_f32 v0, v2, v113
	v_add_f32_e32 v3, v37, v1
	v_add_f32_e32 v1, v53, v1
	ds_write_b16 v184, v0 offset:64
	v_cvt_pk_bf16_f32 v0, v3, v113
	ds_write_b16 v184, v0 offset:128
	v_cvt_pk_bf16_f32 v0, v1, v113
	v_mov_b32_e32 v1, v232
	ds_write_b16 v184, v0 offset:192
	s_waitcnt vmcnt(0)
	v_add_f32_e32 v0, v6, v1
	v_cvt_pk_bf16_f32 v0, v0, v113
	v_add_f32_e32 v2, v22, v1
	ds_write_b16 v185, v0
	v_cvt_pk_bf16_f32 v0, v2, v113
	v_add_f32_e32 v3, v38, v1
	v_add_f32_e32 v1, v54, v1
	ds_write_b16 v185, v0 offset:64
	v_cvt_pk_bf16_f32 v0, v3, v113
	ds_write_b16 v185, v0 offset:128
	v_cvt_pk_bf16_f32 v0, v1, v113
	v_mov_b32_e32 v1, v233
	ds_write_b16 v185, v0 offset:192
	s_waitcnt vmcnt(0)
	v_add_f32_e32 v0, v7, v1
	v_cvt_pk_bf16_f32 v0, v0, v113
	v_add_f32_e32 v2, v23, v1
	ds_write_b16 v186, v0
	v_cvt_pk_bf16_f32 v0, v2, v113
	v_add_f32_e32 v3, v39, v1
	v_add_f32_e32 v1, v55, v1
	ds_write_b16 v186, v0 offset:64
	v_cvt_pk_bf16_f32 v0, v3, v113
	ds_write_b16 v186, v0 offset:128
	v_cvt_pk_bf16_f32 v0, v1, v113
	v_mov_b32_e32 v1, v234
	ds_write_b16 v186, v0 offset:192
	s_waitcnt vmcnt(0)
	v_add_f32_e32 v0, v8, v1
	v_cvt_pk_bf16_f32 v0, v0, v113
	v_add_f32_e32 v2, v24, v1
	ds_write_b16 v187, v0
	v_cvt_pk_bf16_f32 v0, v2, v113
	v_add_f32_e32 v3, v40, v1
	v_add_f32_e32 v1, v56, v1
	ds_write_b16 v187, v0 offset:64
	v_cvt_pk_bf16_f32 v0, v3, v113
	ds_write_b16 v187, v0 offset:128
	v_cvt_pk_bf16_f32 v0, v1, v113
	v_mov_b32_e32 v1, v235
	ds_write_b16 v187, v0 offset:192
	s_waitcnt vmcnt(0)
	v_add_f32_e32 v0, v9, v1
	v_cvt_pk_bf16_f32 v0, v0, v113
	v_add_f32_e32 v2, v25, v1
	ds_write_b16 v188, v0
	v_cvt_pk_bf16_f32 v0, v2, v113
	v_add_f32_e32 v3, v41, v1
	v_add_f32_e32 v1, v57, v1
	ds_write_b16 v188, v0 offset:64
	v_cvt_pk_bf16_f32 v0, v3, v113
	ds_write_b16 v188, v0 offset:128
	v_cvt_pk_bf16_f32 v0, v1, v113
	v_mov_b32_e32 v1, v236
	ds_write_b16 v188, v0 offset:192
	s_waitcnt vmcnt(0)
	v_add_f32_e32 v0, v10, v1
	v_cvt_pk_bf16_f32 v0, v0, v113
	v_add_f32_e32 v2, v26, v1
	ds_write_b16 v189, v0
	v_cvt_pk_bf16_f32 v0, v2, v113
	v_add_f32_e32 v3, v42, v1
	v_add_f32_e32 v1, v58, v1
	ds_write_b16 v189, v0 offset:64
	v_cvt_pk_bf16_f32 v0, v3, v113
	ds_write_b16 v189, v0 offset:128
	v_cvt_pk_bf16_f32 v0, v1, v113
	v_mov_b32_e32 v1, v237
	ds_write_b16 v189, v0 offset:192
	s_waitcnt vmcnt(0)
; __device__ __forceinline__ int crow(int r, int hi) { return (r & 3) + 8 * (r >> 2) + 4 * hi; }
; __device__ __forceinline__ unsigned pk2(float lo, float hi) { return pg8::cvt_pk_bf16(lo, hi); }
; __device__ __forceinline__ float bflo(unsigned w) { return __uint_as_float(w << 16); }
; __device__ __forceinline__ float bfhi(unsigned w) { return __uint_as_float(w & 0xffff0000u); }
; __device__ __forceinline__ void sgu_unit(const Args& a, int l, int unit, unsigned char* ldsg) {
;     ...
;         for (int r = 0; r < 16; ++r) { const int i = iw * 32 + att::crow(r, hi); const float bias = a.in[7][(l * 8 + g) * 128 + i];
; #pragma unroll
;             for (int d0 = 0; d0 < 4; ++d0) *(bf16r*)(lds + OT_OFF + i * OT_PITCH + (eh * 128 + d0 * 32 + r32) * 2) = (bf16r)(pk2(o[d0][r] + bias, 0.f) & 0xffffu); }
;         __syncthreads();
; #pragma unroll
;         for (int k = 0; k < 8; ++k) { const int c = tid + 512 * k, row = c >> 5, cc = c & 31; const size_t gro = (size_t)(row0 + row);
;             const v4u uu = *(const v4u*)(UA + gro * DA + g * 256 + cc * 8), gg = *(const v4u*)(GA + gro * DA + g * 256 + cc * 8), oo = *(const v4u*)(lds + OT_OFF + row * OT_PITCH + cc * 16);
;             v4u w;
;             w.x = pk2(bflo(oo.x) * bflo(uu.x) * bflo(gg.x), bfhi(oo.x) * bfhi(uu.x) * bfhi(gg.x));
;             w.y = pk2(bflo(oo.y) * bflo(uu.y) * bflo(gg.y), bfhi(oo.y) * bfhi(uu.y) * bfhi(gg.y));
;             w.z = pk2(bflo(oo.z) * bflo(uu.z) * bflo(gg.z), bfhi(oo.z) * bfhi(uu.z) * bfhi(gg.z));
;             w.w = pk2(bflo(oo.w) * bflo(uu.w) * bflo(gg.w), bfhi(oo.w) * bfhi(uu.w) * bfhi(gg.w));
;             *(v4u*)(Y + gro * DM + g * 256 + cc * 8) = w; }
	v_add_f32_e32 v0, v11, v1
	v_cvt_pk_bf16_f32 v0, v0, v113
	v_add_f32_e32 v2, v27, v1
	ds_write_b16 v190, v0
	v_cvt_pk_bf16_f32 v0, v2, v113
	v_add_f32_e32 v3, v43, v1
	v_add_f32_e32 v1, v59, v1
	ds_write_b16 v190, v0 offset:64
	v_cvt_pk_bf16_f32 v0, v3, v113
	ds_write_b16 v190, v0 offset:128
	v_cvt_pk_bf16_f32 v0, v1, v113
	v_mov_b32_e32 v1, v238
	ds_write_b16 v190, v0 offset:192
	s_waitcnt vmcnt(0)
	v_add_f32_e32 v0, v12, v1
	v_cvt_pk_bf16_f32 v0, v0, v113
	v_add_f32_e32 v2, v28, v1
	ds_write_b16 v191, v0
	v_cvt_pk_bf16_f32 v0, v2, v113
	v_add_f32_e32 v3, v44, v1
	v_add_f32_e32 v1, v60, v1
	ds_write_b16 v191, v0 offset:64
	v_cvt_pk_bf16_f32 v0, v3, v113
	ds_write_b16 v191, v0 offset:128
	v_cvt_pk_bf16_f32 v0, v1, v113
	v_mov_b32_e32 v1, v239
	ds_write_b16 v191, v0 offset:192
	s_waitcnt vmcnt(0)
	v_add_f32_e32 v0, v13, v1
	v_cvt_pk_bf16_f32 v0, v0, v113
	v_add_f32_e32 v2, v29, v1
	ds_write_b16 v194, v0
	v_cvt_pk_bf16_f32 v0, v2, v113
	v_add_f32_e32 v3, v45, v1
	v_add_f32_e32 v1, v61, v1
	ds_write_b16 v194, v0 offset:64
	v_cvt_pk_bf16_f32 v0, v3, v113
	ds_write_b16 v194, v0 offset:128
	v_cvt_pk_bf16_f32 v0, v1, v113
	v_mov_b32_e32 v1, v240
	ds_write_b16 v194, v0 offset:192
	v_lshl_add_u64 v[12:13], v[130:131], 0, s[24:25]
	s_waitcnt vmcnt(0)
	v_add_f32_e32 v0, v14, v1
	v_cvt_pk_bf16_f32 v0, v0, v113
	v_add_f32_e32 v2, v30, v1
	ds_write_b16 v195, v0
	v_cvt_pk_bf16_f32 v0, v2, v113
	v_add_f32_e32 v3, v46, v1
	v_add_f32_e32 v1, v62, v1
	ds_write_b16 v195, v0 offset:64
	v_cvt_pk_bf16_f32 v0, v3, v113
	ds_write_b16 v195, v0 offset:128
	v_cvt_pk_bf16_f32 v6, v1, v113
	v_mov_b32_e32 v7, v241
	v_lshl_add_u64 v[0:1], v[114:115], 0, s[24:25]
	v_add_co_u32_e32 v2, vcc, s52, v0
	ds_write_b16 v195, v6 offset:192
	s_nop 0
	v_addc_co_u32_e32 v3, vcc, 0, v1, vcc
	v_add_co_u32_e32 v4, vcc, s53, v0
	s_waitcnt vmcnt(0)
	v_add_f32_e32 v0, v15, v7
	v_cvt_pk_bf16_f32 v0, v0, v113
	v_addc_co_u32_e32 v5, vcc, 0, v1, vcc
	v_add_f32_e32 v1, v31, v7
	ds_write_b16 v196, v0
	v_cvt_pk_bf16_f32 v0, v1, v113
	v_add_f32_e32 v6, v47, v7
	ds_write_b16 v196, v0 offset:64
	v_cvt_pk_bf16_f32 v0, v6, v113
	v_add_f32_e32 v7, v63, v7
	ds_write_b16 v196, v0 offset:128
	v_cvt_pk_bf16_f32 v0, v7, v113
	ds_write_b16 v196, v0 offset:192
	s_waitcnt lgkmcnt(0)
	s_barrier
	v_lshl_add_u64 v[30:31], v[114:115], 0, s[24:25]
	v_add_co_u32_e32 v254, vcc, s52, v30
	s_nop 1
	v_addc_co_u32_e32 v255, vcc, 0, v31, vcc
	global_load_dwordx4 v[32:35], v[254:255], off
	s_nop 0
	v_add_co_u32_e32 v254, vcc, s53, v30
	s_nop 1
	v_addc_co_u32_e32 v255, vcc, 0, v31, vcc
	global_load_dwordx4 v[226:229], v[254:255], off
	s_nop 0
	v_lshl_add_u64 v[30:31], v[116:117], 0, s[24:25]
	v_add_co_u32_e32 v254, vcc, s52, v30
	s_nop 1
	v_addc_co_u32_e32 v255, vcc, 0, v31, vcc
	global_load_dwordx4 v[36:39], v[254:255], off
	s_nop 0
	v_add_co_u32_e32 v254, vcc, s53, v30
	s_nop 1
	v_addc_co_u32_e32 v255, vcc, 0, v31, vcc
	global_load_dwordx4 v[230:233], v[254:255], off
	s_nop 0
	v_lshl_add_u64 v[30:31], v[118:119], 0, s[24:25]
	v_add_co_u32_e32 v254, vcc, s52, v30
	s_nop 1
	v_addc_co_u32_e32 v255, vcc, 0, v31, vcc
	global_load_dwordx4 v[40:43], v[254:255], off
	s_nop 0
	v_add_co_u32_e32 v254, vcc, s53, v30
	s_nop 1
	v_addc_co_u32_e32 v255, vcc, 0, v31, vcc
	global_load_dwordx4 v[234:237], v[254:255], off
	s_nop 0
	v_lshl_add_u64 v[30:31], v[120:121], 0, s[24:25]
	v_add_co_u32_e32 v254, vcc, s52, v30
	s_nop 1
	v_addc_co_u32_e32 v255, vcc, 0, v31, vcc
	global_load_dwordx4 v[44:47], v[254:255], off
	s_nop 0
	v_add_co_u32_e32 v254, vcc, s53, v30
	s_nop 1
	v_addc_co_u32_e32 v255, vcc, 0, v31, vcc
	global_load_dwordx4 v[238:241], v[254:255], off
	s_nop 0
	v_lshl_add_u64 v[30:31], v[122:123], 0, s[24:25]
	v_add_co_u32_e32 v254, vcc, s52, v30
	s_nop 1
	v_addc_co_u32_e32 v255, vcc, 0, v31, vcc
	global_load_dwordx4 v[48:51], v[254:255], off
	s_nop 0
	v_add_co_u32_e32 v254, vcc, s53, v30
	s_nop 1
	v_addc_co_u32_e32 v255, vcc, 0, v31, vcc
	global_load_dwordx4 v[242:245], v[254:255], off
	s_nop 0
	v_lshl_add_u64 v[30:31], v[124:125], 0, s[24:25]
	v_add_co_u32_e32 v254, vcc, s52, v30
	s_nop 1
	v_addc_co_u32_e32 v255, vcc, 0, v31, vcc
	global_load_dwordx4 v[52:55], v[254:255], off
	s_nop 0
	v_add_co_u32_e32 v254, vcc, s53, v30
	s_nop 1
	v_addc_co_u32_e32 v255, vcc, 0, v31, vcc
	global_load_dwordx4 v[246:249], v[254:255], off
	s_nop 0
	v_lshl_add_u64 v[30:31], v[126:127], 0, s[24:25]
	v_add_co_u32_e32 v254, vcc, s52, v30
	s_nop 1
	v_addc_co_u32_e32 v255, vcc, 0, v31, vcc
	global_load_dwordx4 v[56:59], v[254:255], off
	s_nop 0
	v_add_co_u32_e32 v254, vcc, s53, v30
	s_nop 1
	v_addc_co_u32_e32 v255, vcc, 0, v31, vcc
	global_load_dwordx4 v[250:253], v[254:255], off
	s_nop 0
	v_lshl_add_u64 v[30:31], v[128:129], 0, s[24:25]
	v_add_co_u32_e32 v254, vcc, s52, v30
	s_nop 1
	v_addc_co_u32_e32 v255, vcc, 0, v31, vcc
	global_load_dwordx4 v[60:63], v[254:255], off
	s_nop 0
	v_add_co_u32_e32 v254, vcc, s53, v30
	s_nop 1
	v_addc_co_u32_e32 v255, vcc, 0, v31, vcc
	global_load_dwordx4 v[64:67], v[254:255], off
	s_nop 0
	s_nop 0
	ds_read_b128 v[8:11], v197
	v_lshl_add_u64 v[14:15], v[116:117], 0, s[24:25]
	v_add_co_u32_e32 v16, vcc, s52, v14
	s_waitcnt lgkmcnt(0)
	v_lshlrev_b32_e32 v18, 16, v8
	v_and_b32_e32 v8, 0xffff0000, v8
	v_lshlrev_b32_e32 v19, 16, v9
	v_and_b32_e32 v9, 0xffff0000, v9
	v_lshlrev_b32_e32 v20, 16, v10
	v_and_b32_e32 v10, 0xffff0000, v10
	v_lshlrev_b32_e32 v21, 16, v11
	v_and_b32_e32 v11, 0xffff0000, v11
	v_addc_co_u32_e32 v17, vcc, 0, v15, vcc
	v_add_co_u32_e32 v14, vcc, s53, v14
	s_waitcnt vmcnt(14)
; __device__ __forceinline__ unsigned pk2(float lo, float hi) { return pg8::cvt_pk_bf16(lo, hi); }
; __device__ __forceinline__ float bflo(unsigned w) { return __uint_as_float(w << 16); }
; __device__ __forceinline__ float bfhi(unsigned w) { return __uint_as_float(w & 0xffff0000u); }
; __device__ __forceinline__ void sgu_unit(const Args& a, int l, int unit, unsigned char* ldsg) {
;     ...
;         for (int k = 0; k < 8; ++k) { const int c = tid + 512 * k, row = c >> 5, cc = c & 31; const size_t gro = (size_t)(row0 + row);
;             const v4u uu = *(const v4u*)(UA + gro * DA + g * 256 + cc * 8), gg = *(const v4u*)(GA + gro * DA + g * 256 + cc * 8), oo = *(const v4u*)(lds + OT_OFF + row * OT_PITCH + cc * 16);
;             v4u w;
;             w.x = pk2(bflo(oo.x) * bflo(uu.x) * bflo(gg.x), bfhi(oo.x) * bfhi(uu.x) * bfhi(gg.x));
;             w.y = pk2(bflo(oo.y) * bflo(uu.y) * bflo(gg.y), bfhi(oo.y) * bfhi(uu.y) * bfhi(gg.y));
;             w.z = pk2(bflo(oo.z) * bflo(uu.z) * bflo(gg.z), bfhi(oo.z) * bfhi(uu.z) * bfhi(gg.z));
;             w.w = pk2(bflo(oo.w) * bflo(uu.w) * bflo(gg.w), bfhi(oo.w) * bfhi(uu.w) * bfhi(gg.w));
;             *(v4u*)(Y + gro * DM + g * 256 + cc * 8) = w; }
	v_mov_b32_e32 v0, v32
	v_mov_b32_e32 v1, v33
	v_mov_b32_e32 v2, v34
	v_mov_b32_e32 v3, v35
	v_mov_b32_e32 v4, v226
	v_mov_b32_e32 v5, v227
	v_mov_b32_e32 v6, v228
	v_mov_b32_e32 v7, v229
	v_lshlrev_b32_e32 v22, 16, v0
	v_and_b32_e32 v0, 0xffff0000, v0
	v_lshlrev_b32_e32 v24, 16, v1
	v_and_b32_e32 v1, 0xffff0000, v1
	v_lshlrev_b32_e32 v26, 16, v2
	v_and_b32_e32 v2, 0xffff0000, v2
	v_lshlrev_b32_e32 v28, 16, v3
	v_and_b32_e32 v3, 0xffff0000, v3
	v_lshlrev_b32_e32 v23, 16, v4
	v_and_b32_e32 v4, 0xffff0000, v4
	v_lshlrev_b32_e32 v25, 16, v5
	v_and_b32_e32 v5, 0xffff0000, v5
	v_lshlrev_b32_e32 v27, 16, v6
	v_and_b32_e32 v6, 0xffff0000, v6
	v_lshlrev_b32_e32 v29, 16, v7
	v_and_b32_e32 v7, 0xffff0000, v7
	v_mul_f32_e32 v0, v8, v0
	v_mul_f32_e32 v1, v9, v1
	v_mul_f32_e32 v2, v10, v2
	v_mul_f32_e32 v3, v11, v3
	v_mul_f32_e32 v18, v18, v22
	v_mul_f32_e32 v8, v19, v24
	v_mul_f32_e32 v9, v20, v26
	v_mul_f32_e32 v10, v21, v28
	v_mul_f32_e32 v0, v0, v4
	v_mul_f32_e32 v1, v1, v5
	v_mul_f32_e32 v2, v2, v6
	v_mul_f32_e32 v3, v3, v7
	v_mul_f32_e32 v11, v18, v23
	v_mul_f32_e32 v4, v8, v25
	v_mul_f32_e32 v5, v9, v27
	v_mul_f32_e32 v6, v10, v29
	v_cvt_pk_bf16_f32 v0, v11, v0
	v_cvt_pk_bf16_f32 v1, v4, v1
	v_cvt_pk_bf16_f32 v2, v5, v2
	v_cvt_pk_bf16_f32 v3, v6, v3
	global_store_dwordx4 v[12:13], v[0:3], off
	v_addc_co_u32_e32 v15, vcc, 0, v15, vcc
	ds_read_b128 v[8:11], v198
	v_lshl_add_u64 v[14:15], v[118:119], 0, s[24:25]
	v_add_co_u32_e32 v16, vcc, s52, v14
	v_lshl_add_u64 v[12:13], v[132:133], 0, s[24:25]
	s_waitcnt lgkmcnt(0)
	v_lshlrev_b32_e32 v18, 16, v8
	v_and_b32_e32 v8, 0xffff0000, v8
	v_lshlrev_b32_e32 v19, 16, v9
	v_and_b32_e32 v9, 0xffff0000, v9
	v_lshlrev_b32_e32 v20, 16, v10
	v_and_b32_e32 v10, 0xffff0000, v10
	v_lshlrev_b32_e32 v21, 16, v11
	v_and_b32_e32 v11, 0xffff0000, v11
	v_addc_co_u32_e32 v17, vcc, 0, v15, vcc
	v_add_co_u32_e32 v14, vcc, s53, v14
	s_waitcnt vmcnt(13)
	v_mov_b32_e32 v0, v36
	v_mov_b32_e32 v1, v37
	v_mov_b32_e32 v2, v38
	v_mov_b32_e32 v3, v39
	v_mov_b32_e32 v4, v230
	v_mov_b32_e32 v5, v231
	v_mov_b32_e32 v6, v232
	v_mov_b32_e32 v7, v233
	v_lshlrev_b32_e32 v22, 16, v0
	v_and_b32_e32 v0, 0xffff0000, v0
	v_lshlrev_b32_e32 v24, 16, v1
	v_and_b32_e32 v1, 0xffff0000, v1
	v_lshlrev_b32_e32 v26, 16, v2
	v_and_b32_e32 v2, 0xffff0000, v2
	v_lshlrev_b32_e32 v28, 16, v3
	v_and_b32_e32 v3, 0xffff0000, v3
	v_lshlrev_b32_e32 v23, 16, v4
	v_and_b32_e32 v4, 0xffff0000, v4
	v_lshlrev_b32_e32 v25, 16, v5
	v_and_b32_e32 v5, 0xffff0000, v5
	v_lshlrev_b32_e32 v27, 16, v6
	v_and_b32_e32 v6, 0xffff0000, v6
	v_lshlrev_b32_e32 v29, 16, v7
	v_and_b32_e32 v7, 0xffff0000, v7
	v_mul_f32_e32 v0, v8, v0
	v_mul_f32_e32 v1, v9, v1
	v_mul_f32_e32 v2, v10, v2
	v_mul_f32_e32 v3, v11, v3
	v_mul_f32_e32 v18, v18, v22
	v_mul_f32_e32 v8, v19, v24
	v_mul_f32_e32 v9, v20, v26
	v_mul_f32_e32 v10, v21, v28
	v_mul_f32_e32 v0, v0, v4
	v_mul_f32_e32 v1, v1, v5
	v_mul_f32_e32 v2, v2, v6
	v_mul_f32_e32 v3, v3, v7
	v_mul_f32_e32 v11, v18, v23
	v_mul_f32_e32 v4, v8, v25
	v_mul_f32_e32 v5, v9, v27
	v_mul_f32_e32 v6, v10, v29
	v_cvt_pk_bf16_f32 v0, v11, v0
	v_cvt_pk_bf16_f32 v1, v4, v1
	v_cvt_pk_bf16_f32 v2, v5, v2
	v_cvt_pk_bf16_f32 v3, v6, v3
	global_store_dwordx4 v[12:13], v[0:3], off
	v_addc_co_u32_e32 v15, vcc, 0, v15, vcc
	ds_read_b128 v[8:11], v199
	v_lshl_add_u64 v[14:15], v[120:121], 0, s[24:25]
	v_add_co_u32_e32 v16, vcc, s52, v14
	v_lshl_add_u64 v[12:13], v[134:135], 0, s[24:25]
	s_waitcnt lgkmcnt(0)
	v_lshlrev_b32_e32 v18, 16, v8
	v_and_b32_e32 v8, 0xffff0000, v8
	v_lshlrev_b32_e32 v19, 16, v9
	v_and_b32_e32 v9, 0xffff0000, v9
	v_lshlrev_b32_e32 v20, 16, v10
	v_and_b32_e32 v10, 0xffff0000, v10
	v_lshlrev_b32_e32 v21, 16, v11
	v_and_b32_e32 v11, 0xffff0000, v11
	v_addc_co_u32_e32 v17, vcc, 0, v15, vcc
	v_add_co_u32_e32 v14, vcc, s53, v14
	s_waitcnt vmcnt(12)
	v_mov_b32_e32 v0, v40
	v_mov_b32_e32 v1, v41
	v_mov_b32_e32 v2, v42
	v_mov_b32_e32 v3, v43
	v_mov_b32_e32 v4, v234
	v_mov_b32_e32 v5, v235
	v_mov_b32_e32 v6, v236
	v_mov_b32_e32 v7, v237
	v_lshlrev_b32_e32 v22, 16, v0
	v_and_b32_e32 v0, 0xffff0000, v0
	v_lshlrev_b32_e32 v24, 16, v1
	v_and_b32_e32 v1, 0xffff0000, v1
	v_lshlrev_b32_e32 v26, 16, v2
	v_and_b32_e32 v2, 0xffff0000, v2
	v_lshlrev_b32_e32 v28, 16, v3
	v_and_b32_e32 v3, 0xffff0000, v3
	v_lshlrev_b32_e32 v23, 16, v4
	v_and_b32_e32 v4, 0xffff0000, v4
	v_lshlrev_b32_e32 v25, 16, v5
	v_and_b32_e32 v5, 0xffff0000, v5
	v_lshlrev_b32_e32 v27, 16, v6
	v_and_b32_e32 v6, 0xffff0000, v6
	v_lshlrev_b32_e32 v29, 16, v7
	v_and_b32_e32 v7, 0xffff0000, v7
	v_mul_f32_e32 v0, v8, v0
	v_mul_f32_e32 v1, v9, v1
	v_mul_f32_e32 v2, v10, v2
	v_mul_f32_e32 v3, v11, v3
	v_mul_f32_e32 v18, v18, v22
	v_mul_f32_e32 v8, v19, v24
	v_mul_f32_e32 v9, v20, v26
	v_mul_f32_e32 v10, v21, v28
	v_mul_f32_e32 v0, v0, v4
	v_mul_f32_e32 v1, v1, v5
	v_mul_f32_e32 v2, v2, v6
	v_mul_f32_e32 v3, v3, v7
	v_mul_f32_e32 v11, v18, v23
	v_mul_f32_e32 v4, v8, v25
	v_mul_f32_e32 v5, v9, v27
	v_mul_f32_e32 v6, v10, v29
	v_cvt_pk_bf16_f32 v0, v11, v0
	v_cvt_pk_bf16_f32 v1, v4, v1
	v_cvt_pk_bf16_f32 v2, v5, v2
	v_cvt_pk_bf16_f32 v3, v6, v3
	global_store_dwordx4 v[12:13], v[0:3], off
	v_addc_co_u32_e32 v15, vcc, 0, v15, vcc
	ds_read_b128 v[8:11], v200
	v_lshl_add_u64 v[14:15], v[122:123], 0, s[24:25]
	v_add_co_u32_e32 v16, vcc, s52, v14
	v_lshl_add_u64 v[12:13], v[136:137], 0, s[24:25]
	s_waitcnt lgkmcnt(0)
	v_lshlrev_b32_e32 v18, 16, v8
	v_and_b32_e32 v8, 0xffff0000, v8
	v_lshlrev_b32_e32 v19, 16, v9
	v_and_b32_e32 v9, 0xffff0000, v9
	v_lshlrev_b32_e32 v20, 16, v10
	v_and_b32_e32 v10, 0xffff0000, v10
	v_lshlrev_b32_e32 v21, 16, v11
	v_and_b32_e32 v11, 0xffff0000, v11
	v_addc_co_u32_e32 v17, vcc, 0, v15, vcc
	v_add_co_u32_e32 v14, vcc, s53, v14
	s_waitcnt vmcnt(11)
; __device__ __forceinline__ unsigned pk2(float lo, float hi) { return pg8::cvt_pk_bf16(lo, hi); }
; __device__ __forceinline__ float bflo(unsigned w) { return __uint_as_float(w << 16); }
; __device__ __forceinline__ float bfhi(unsigned w) { return __uint_as_float(w & 0xffff0000u); }
; __device__ __forceinline__ void sgu_unit(const Args& a, int l, int unit, unsigned char* ldsg) {
;     ...
;         for (int k = 0; k < 8; ++k) { const int c = tid + 512 * k, row = c >> 5, cc = c & 31; const size_t gro = (size_t)(row0 + row);
;             const v4u uu = *(const v4u*)(UA + gro * DA + g * 256 + cc * 8), gg = *(const v4u*)(GA + gro * DA + g * 256 + cc * 8), oo = *(const v4u*)(lds + OT_OFF + row * OT_PITCH + cc * 16);
;             v4u w;
;             w.x = pk2(bflo(oo.x) * bflo(uu.x) * bflo(gg.x), bfhi(oo.x) * bfhi(uu.x) * bfhi(gg.x));
;             w.y = pk2(bflo(oo.y) * bflo(uu.y) * bflo(gg.y), bfhi(oo.y) * bfhi(uu.y) * bfhi(gg.y));
;             w.z = pk2(bflo(oo.z) * bflo(uu.z) * bflo(gg.z), bfhi(oo.z) * bfhi(uu.z) * bfhi(gg.z));
;             w.w = pk2(bflo(oo.w) * bflo(uu.w) * bflo(gg.w), bfhi(oo.w) * bfhi(uu.w) * bfhi(gg.w));
;             *(v4u*)(Y + gro * DM + g * 256 + cc * 8) = w; }
	v_mov_b32_e32 v0, v44
	v_mov_b32_e32 v1, v45
	v_mov_b32_e32 v2, v46
	v_mov_b32_e32 v3, v47
	v_mov_b32_e32 v4, v238
	v_mov_b32_e32 v5, v239
	v_mov_b32_e32 v6, v240
	v_mov_b32_e32 v7, v241
	v_lshlrev_b32_e32 v22, 16, v0
	v_and_b32_e32 v0, 0xffff0000, v0
	v_lshlrev_b32_e32 v24, 16, v1
	v_and_b32_e32 v1, 0xffff0000, v1
	v_lshlrev_b32_e32 v26, 16, v2
	v_and_b32_e32 v2, 0xffff0000, v2
	v_lshlrev_b32_e32 v28, 16, v3
	v_and_b32_e32 v3, 0xffff0000, v3
	v_lshlrev_b32_e32 v23, 16, v4
	v_and_b32_e32 v4, 0xffff0000, v4
	v_lshlrev_b32_e32 v25, 16, v5
	v_and_b32_e32 v5, 0xffff0000, v5
	v_lshlrev_b32_e32 v27, 16, v6
	v_and_b32_e32 v6, 0xffff0000, v6
	v_lshlrev_b32_e32 v29, 16, v7
	v_and_b32_e32 v7, 0xffff0000, v7
	v_mul_f32_e32 v0, v8, v0
	v_mul_f32_e32 v1, v9, v1
	v_mul_f32_e32 v2, v10, v2
	v_mul_f32_e32 v3, v11, v3
	v_mul_f32_e32 v18, v18, v22
	v_mul_f32_e32 v8, v19, v24
	v_mul_f32_e32 v9, v20, v26
	v_mul_f32_e32 v10, v21, v28
	v_mul_f32_e32 v0, v0, v4
	v_mul_f32_e32 v1, v1, v5
	v_mul_f32_e32 v2, v2, v6
	v_mul_f32_e32 v3, v3, v7
	v_mul_f32_e32 v11, v18, v23
	v_mul_f32_e32 v4, v8, v25
	v_mul_f32_e32 v5, v9, v27
	v_mul_f32_e32 v6, v10, v29
	v_cvt_pk_bf16_f32 v0, v11, v0
	v_cvt_pk_bf16_f32 v1, v4, v1
	v_cvt_pk_bf16_f32 v2, v5, v2
	v_cvt_pk_bf16_f32 v3, v6, v3
	global_store_dwordx4 v[12:13], v[0:3], off
	v_addc_co_u32_e32 v15, vcc, 0, v15, vcc
	ds_read_b128 v[8:11], v201
	v_lshl_add_u64 v[14:15], v[124:125], 0, s[24:25]
	v_add_co_u32_e32 v16, vcc, s52, v14
	v_lshl_add_u64 v[12:13], v[138:139], 0, s[24:25]
	s_waitcnt lgkmcnt(0)
	v_lshlrev_b32_e32 v18, 16, v8
	v_and_b32_e32 v8, 0xffff0000, v8
	v_lshlrev_b32_e32 v19, 16, v9
	v_and_b32_e32 v9, 0xffff0000, v9
	v_lshlrev_b32_e32 v20, 16, v10
	v_and_b32_e32 v10, 0xffff0000, v10
	v_lshlrev_b32_e32 v21, 16, v11
	v_and_b32_e32 v11, 0xffff0000, v11
	v_addc_co_u32_e32 v17, vcc, 0, v15, vcc
	v_add_co_u32_e32 v14, vcc, s53, v14
	s_waitcnt vmcnt(10)
	v_mov_b32_e32 v0, v48
	v_mov_b32_e32 v1, v49
	v_mov_b32_e32 v2, v50
	v_mov_b32_e32 v3, v51
	v_mov_b32_e32 v4, v242
	v_mov_b32_e32 v5, v243
	v_mov_b32_e32 v6, v244
	v_mov_b32_e32 v7, v245
	v_lshlrev_b32_e32 v22, 16, v0
	v_and_b32_e32 v0, 0xffff0000, v0
	v_lshlrev_b32_e32 v24, 16, v1
	v_and_b32_e32 v1, 0xffff0000, v1
	v_lshlrev_b32_e32 v26, 16, v2
	v_and_b32_e32 v2, 0xffff0000, v2
	v_lshlrev_b32_e32 v28, 16, v3
	v_and_b32_e32 v3, 0xffff0000, v3
	v_lshlrev_b32_e32 v23, 16, v4
	v_and_b32_e32 v4, 0xffff0000, v4
	v_lshlrev_b32_e32 v25, 16, v5
	v_and_b32_e32 v5, 0xffff0000, v5
	v_lshlrev_b32_e32 v27, 16, v6
	v_and_b32_e32 v6, 0xffff0000, v6
	v_lshlrev_b32_e32 v29, 16, v7
	v_and_b32_e32 v7, 0xffff0000, v7
	v_mul_f32_e32 v0, v8, v0
	v_mul_f32_e32 v1, v9, v1
	v_mul_f32_e32 v2, v10, v2
	v_mul_f32_e32 v3, v11, v3
	v_mul_f32_e32 v18, v18, v22
	v_mul_f32_e32 v8, v19, v24
	v_mul_f32_e32 v9, v20, v26
	v_mul_f32_e32 v10, v21, v28
	v_mul_f32_e32 v0, v0, v4
	v_mul_f32_e32 v1, v1, v5
	v_mul_f32_e32 v2, v2, v6
	v_mul_f32_e32 v3, v3, v7
	v_mul_f32_e32 v11, v18, v23
	v_mul_f32_e32 v4, v8, v25
	v_mul_f32_e32 v5, v9, v27
	v_mul_f32_e32 v6, v10, v29
	v_cvt_pk_bf16_f32 v0, v11, v0
	v_cvt_pk_bf16_f32 v1, v4, v1
	v_cvt_pk_bf16_f32 v2, v5, v2
	v_cvt_pk_bf16_f32 v3, v6, v3
	global_store_dwordx4 v[12:13], v[0:3], off
	v_addc_co_u32_e32 v15, vcc, 0, v15, vcc
	ds_read_b128 v[8:11], v202
	v_lshl_add_u64 v[14:15], v[126:127], 0, s[24:25]
	v_add_co_u32_e32 v16, vcc, s52, v14
	v_lshl_add_u64 v[12:13], v[140:141], 0, s[24:25]
	s_waitcnt lgkmcnt(0)
	v_lshlrev_b32_e32 v18, 16, v8
	v_and_b32_e32 v8, 0xffff0000, v8
	v_lshlrev_b32_e32 v19, 16, v9
	v_and_b32_e32 v9, 0xffff0000, v9
	v_lshlrev_b32_e32 v20, 16, v10
	v_and_b32_e32 v10, 0xffff0000, v10
	v_lshlrev_b32_e32 v21, 16, v11
	v_and_b32_e32 v11, 0xffff0000, v11
	v_addc_co_u32_e32 v17, vcc, 0, v15, vcc
	v_add_co_u32_e32 v14, vcc, s53, v14
	s_waitcnt vmcnt(9)
; __device__ __forceinline__ unsigned pk2(float lo, float hi) { return pg8::cvt_pk_bf16(lo, hi); }
; __device__ __forceinline__ float bflo(unsigned w) { return __uint_as_float(w << 16); }
; __device__ __forceinline__ float bfhi(unsigned w) { return __uint_as_float(w & 0xffff0000u); }
; __device__ __forceinline__ void sgu_unit(const Args& a, int l, int unit, unsigned char* ldsg) {
;     ...
;         for (int k = 0; k < 8; ++k) { const int c = tid + 512 * k, row = c >> 5, cc = c & 31; const size_t gro = (size_t)(row0 + row);
;             const v4u uu = *(const v4u*)(UA + gro * DA + g * 256 + cc * 8), gg = *(const v4u*)(GA + gro * DA + g * 256 + cc * 8), oo = *(const v4u*)(lds + OT_OFF + row * OT_PITCH + cc * 16);
;             v4u w;
;             w.x = pk2(bflo(oo.x) * bflo(uu.x) * bflo(gg.x), bfhi(oo.x) * bfhi(uu.x) * bfhi(gg.x));
;             w.y = pk2(bflo(oo.y) * bflo(uu.y) * bflo(gg.y), bfhi(oo.y) * bfhi(uu.y) * bfhi(gg.y));
;             w.z = pk2(bflo(oo.z) * bflo(uu.z) * bflo(gg.z), bfhi(oo.z) * bfhi(uu.z) * bfhi(gg.z));
;             w.w = pk2(bflo(oo.w) * bflo(uu.w) * bflo(gg.w), bfhi(oo.w) * bfhi(uu.w) * bfhi(gg.w));
;             *(v4u*)(Y + gro * DM + g * 256 + cc * 8) = w; }
	v_mov_b32_e32 v0, v52
	v_mov_b32_e32 v1, v53
	v_mov_b32_e32 v2, v54
	v_mov_b32_e32 v3, v55
	v_mov_b32_e32 v4, v246
	v_mov_b32_e32 v5, v247
	v_mov_b32_e32 v6, v248
	v_mov_b32_e32 v7, v249
	v_lshlrev_b32_e32 v22, 16, v0
	v_and_b32_e32 v0, 0xffff0000, v0
	v_lshlrev_b32_e32 v24, 16, v1
	v_and_b32_e32 v1, 0xffff0000, v1
	v_lshlrev_b32_e32 v26, 16, v2
	v_and_b32_e32 v2, 0xffff0000, v2
	v_lshlrev_b32_e32 v28, 16, v3
	v_and_b32_e32 v3, 0xffff0000, v3
	v_lshlrev_b32_e32 v23, 16, v4
	v_and_b32_e32 v4, 0xffff0000, v4
	v_lshlrev_b32_e32 v25, 16, v5
	v_and_b32_e32 v5, 0xffff0000, v5
	v_lshlrev_b32_e32 v27, 16, v6
	v_and_b32_e32 v6, 0xffff0000, v6
	v_lshlrev_b32_e32 v29, 16, v7
	v_and_b32_e32 v7, 0xffff0000, v7
	v_mul_f32_e32 v0, v8, v0
	v_mul_f32_e32 v1, v9, v1
	v_mul_f32_e32 v2, v10, v2
	v_mul_f32_e32 v3, v11, v3
	v_mul_f32_e32 v18, v18, v22
	v_mul_f32_e32 v8, v19, v24
	v_mul_f32_e32 v9, v20, v26
	v_mul_f32_e32 v10, v21, v28
	v_mul_f32_e32 v0, v0, v4
	v_mul_f32_e32 v1, v1, v5
	v_mul_f32_e32 v2, v2, v6
	v_mul_f32_e32 v3, v3, v7
	v_mul_f32_e32 v11, v18, v23
	v_mul_f32_e32 v4, v8, v25
	v_mul_f32_e32 v5, v9, v27
	v_mul_f32_e32 v6, v10, v29
	v_cvt_pk_bf16_f32 v0, v11, v0
	v_cvt_pk_bf16_f32 v1, v4, v1
	v_cvt_pk_bf16_f32 v2, v5, v2
	v_cvt_pk_bf16_f32 v3, v6, v3
	global_store_dwordx4 v[12:13], v[0:3], off
	v_addc_co_u32_e32 v15, vcc, 0, v15, vcc
	ds_read_b128 v[8:11], v203
	v_lshl_add_u64 v[14:15], v[128:129], 0, s[24:25]
	v_add_co_u32_e32 v16, vcc, s52, v14
	v_lshl_add_u64 v[12:13], v[142:143], 0, s[24:25]
	s_waitcnt lgkmcnt(0)
	v_lshlrev_b32_e32 v18, 16, v8
	v_and_b32_e32 v8, 0xffff0000, v8
	v_lshlrev_b32_e32 v19, 16, v9
	v_and_b32_e32 v9, 0xffff0000, v9
	v_lshlrev_b32_e32 v20, 16, v10
	v_and_b32_e32 v10, 0xffff0000, v10
	v_lshlrev_b32_e32 v21, 16, v11
	v_and_b32_e32 v11, 0xffff0000, v11
	v_addc_co_u32_e32 v17, vcc, 0, v15, vcc
	v_add_co_u32_e32 v14, vcc, s53, v14
	s_waitcnt vmcnt(8)
	v_mov_b32_e32 v0, v56
	v_mov_b32_e32 v1, v57
	v_mov_b32_e32 v2, v58
	v_mov_b32_e32 v3, v59
	v_mov_b32_e32 v4, v250
	v_mov_b32_e32 v5, v251
	v_mov_b32_e32 v6, v252
	v_mov_b32_e32 v7, v253
	v_lshlrev_b32_e32 v22, 16, v0
	v_and_b32_e32 v0, 0xffff0000, v0
	v_lshlrev_b32_e32 v24, 16, v1
	v_and_b32_e32 v1, 0xffff0000, v1
	v_lshlrev_b32_e32 v26, 16, v2
	v_and_b32_e32 v2, 0xffff0000, v2
	v_lshlrev_b32_e32 v28, 16, v3
	v_and_b32_e32 v3, 0xffff0000, v3
	v_lshlrev_b32_e32 v23, 16, v4
	v_and_b32_e32 v4, 0xffff0000, v4
	v_lshlrev_b32_e32 v25, 16, v5
	v_and_b32_e32 v5, 0xffff0000, v5
	v_lshlrev_b32_e32 v27, 16, v6
	v_and_b32_e32 v6, 0xffff0000, v6
	v_lshlrev_b32_e32 v29, 16, v7
	v_and_b32_e32 v7, 0xffff0000, v7
	v_mul_f32_e32 v0, v8, v0
	v_mul_f32_e32 v1, v9, v1
	v_mul_f32_e32 v2, v10, v2
	v_mul_f32_e32 v3, v11, v3
	v_mul_f32_e32 v18, v18, v22
	v_mul_f32_e32 v8, v19, v24
	v_mul_f32_e32 v9, v20, v26
	v_mul_f32_e32 v10, v21, v28
	v_mul_f32_e32 v0, v0, v4
	v_mul_f32_e32 v1, v1, v5
	v_mul_f32_e32 v2, v2, v6
	v_mul_f32_e32 v3, v3, v7
	v_mul_f32_e32 v11, v18, v23
	v_mul_f32_e32 v4, v8, v25
	v_mul_f32_e32 v5, v9, v27
	v_mul_f32_e32 v6, v10, v29
	v_cvt_pk_bf16_f32 v0, v11, v0
	v_cvt_pk_bf16_f32 v1, v4, v1
	v_cvt_pk_bf16_f32 v2, v5, v2
	v_cvt_pk_bf16_f32 v3, v6, v3
	global_store_dwordx4 v[12:13], v[0:3], off
	v_addc_co_u32_e32 v15, vcc, 0, v15, vcc
	ds_read_b128 v[8:11], v204
	v_lshl_add_u64 v[12:13], v[144:145], 0, s[24:25]
	s_add_u32 s24, s24, 0x200
	s_addc_u32 s25, s25, 0
	s_add_u32 s38, s38, 0x400
	s_addc_u32 s39, s39, 0
	s_add_u32 s26, s26, 0x400
	s_waitcnt lgkmcnt(0)
	v_lshlrev_b32_e32 v14, 16, v8
	v_and_b32_e32 v8, 0xffff0000, v8
	v_lshlrev_b32_e32 v15, 16, v9
	v_and_b32_e32 v9, 0xffff0000, v9
	v_lshlrev_b32_e32 v16, 16, v10
	v_and_b32_e32 v10, 0xffff0000, v10
	v_lshlrev_b32_e32 v17, 16, v11
	v_and_b32_e32 v11, 0xffff0000, v11
	s_addc_u32 s27, s27, 0
	s_cmpk_lg_i32 s24, 0x800
	s_waitcnt vmcnt(7)
	v_mov_b32_e32 v0, v60
	v_mov_b32_e32 v1, v61
	v_mov_b32_e32 v2, v62
	v_mov_b32_e32 v3, v63
	v_mov_b32_e32 v4, v64
	v_mov_b32_e32 v5, v65
	v_mov_b32_e32 v6, v66
	v_mov_b32_e32 v7, v67
	v_lshlrev_b32_e32 v18, 16, v0
	v_and_b32_e32 v0, 0xffff0000, v0
	v_lshlrev_b32_e32 v20, 16, v1
	v_and_b32_e32 v1, 0xffff0000, v1
	v_lshlrev_b32_e32 v22, 16, v2
	v_and_b32_e32 v2, 0xffff0000, v2
	v_lshlrev_b32_e32 v24, 16, v3
	v_and_b32_e32 v3, 0xffff0000, v3
	v_lshlrev_b32_e32 v19, 16, v4
	v_and_b32_e32 v4, 0xffff0000, v4
	v_lshlrev_b32_e32 v21, 16, v5
	v_and_b32_e32 v5, 0xffff0000, v5
	v_lshlrev_b32_e32 v23, 16, v6
	v_and_b32_e32 v6, 0xffff0000, v6
	v_lshlrev_b32_e32 v25, 16, v7
	v_and_b32_e32 v7, 0xffff0000, v7
	v_mul_f32_e32 v0, v8, v0
	v_mul_f32_e32 v1, v9, v1
	v_mul_f32_e32 v2, v10, v2
	v_mul_f32_e32 v3, v11, v3
	v_mul_f32_e32 v14, v14, v18
	v_mul_f32_e32 v8, v15, v20
	v_mul_f32_e32 v9, v16, v22
	v_mul_f32_e32 v10, v17, v24
	v_mul_f32_e32 v0, v0, v4
	v_mul_f32_e32 v1, v1, v5
	v_mul_f32_e32 v2, v2, v6
	v_mul_f32_e32 v3, v3, v7
	v_mul_f32_e32 v11, v14, v19
	v_mul_f32_e32 v4, v8, v21
	v_mul_f32_e32 v5, v9, v23
	v_mul_f32_e32 v6, v10, v25
	v_cvt_pk_bf16_f32 v0, v11, v0
	v_cvt_pk_bf16_f32 v1, v4, v1
	v_cvt_pk_bf16_f32 v2, v5, v2
	v_cvt_pk_bf16_f32 v3, v6, v3
	global_store_dwordx4 v[12:13], v[0:3], off
	s_cbranch_scc0 .LBB0_318

; __device__ __forceinline__ int crow(int r, int hi) { return (r & 3) + 8 * (r >> 2) + 4 * hi; }
; __device__ __forceinline__ unsigned pk2(float lo, float hi) { return pg8::cvt_pk_bf16(lo, hi); }
; __device__ __forceinline__ void sgu_unit(const Args& a, int l, int unit, unsigned char* ldsg) {
;     ...
; #pragma unroll
;         for (int r = 0; r < 16; ++r) { const int i = iw * 32 + att::crow(r, hi); const float bias = a.in[7][(l * 8 + g) * 128 + i];
; #pragma unroll
;             for (int d0 = 0; d0 < 4; ++d0) *(bf16r*)(lds + OT_OFF + i * OT_PITCH + (eh * 128 + d0 * 32 + r32) * 2) = (bf16r)(pk2(o[d0][r] + bias, 0.f) & 0xffffu); }
.LBB0_933:
	v_lshl_add_u64 v[64:65], v[170:171], 0, s[38:39]
	v_lshl_add_u64 v[242:243], v[170:171], 0, s[38:39]
	global_load_dword v226, v[242:243], off
	global_load_dword v227, v[242:243], off offset:4
	global_load_dword v228, v[242:243], off offset:8
	global_load_dword v229, v[242:243], off offset:12
	v_lshl_add_u64 v[244:245], v[178:179], 0, s[38:39]
	global_load_dword v230, v[244:245], off
	global_load_dword v231, v[244:245], off offset:4
	global_load_dword v232, v[244:245], off offset:8
	global_load_dword v233, v[244:245], off offset:12
	v_lshl_add_u64 v[246:247], v[176:177], 0, s[38:39]
	global_load_dword v234, v[246:247], off
	global_load_dword v235, v[246:247], off offset:4
	global_load_dword v236, v[246:247], off offset:8
	global_load_dword v237, v[246:247], off offset:12
	v_lshl_add_u64 v[248:249], v[174:175], 0, s[38:39]
	global_load_dword v238, v[248:249], off
	global_load_dword v239, v[248:249], off offset:4
	global_load_dword v240, v[248:249], off offset:8
	global_load_dword v241, v[248:249], off offset:12
	s_waitcnt vmcnt(0)
	v_mov_b32_e32 v66, v226
	v_add_u32_e32 v67, v191, v190
	v_lshl_add_u64 v[172:173], v[172:173], 0, s[24:25]
	s_waitcnt vmcnt(0)
	v_add_f32_e32 v0, v0, v66
	v_cvt_pk_bf16_f32 v0, v0, v113
	v_add_f32_e32 v16, v16, v66
	ds_write_b16 v67, v0
	v_cvt_pk_bf16_f32 v0, v16, v113
	v_add_f32_e32 v32, v32, v66
	ds_write_b16 v67, v0 offset:64
	v_cvt_pk_bf16_f32 v0, v32, v113
	s_nop 0
	v_add_f32_e32 v48, v48, v66
	ds_write_b16 v67, v0 offset:128
	v_cvt_pk_bf16_f32 v0, v48, v113
	v_mov_b32_e32 v16, v227
	ds_write_b16 v67, v0 offset:192
	s_waitcnt vmcnt(0)
	v_add_f32_e32 v0, v1, v16
	v_cvt_pk_bf16_f32 v0, v0, v113
	v_add_f32_e32 v1, v17, v16
	ds_write_b16 v195, v0
	v_cvt_pk_bf16_f32 v0, v1, v113
	v_add_f32_e32 v17, v33, v16
	ds_write_b16 v195, v0 offset:64
	v_cvt_pk_bf16_f32 v0, v17, v113
	v_add_f32_e32 v16, v49, v16
	ds_write_b16 v195, v0 offset:128
	v_cvt_pk_bf16_f32 v0, v16, v113
	v_mov_b32_e32 v1, v228
	ds_write_b16 v195, v0 offset:192
	s_waitcnt vmcnt(0)
	v_add_f32_e32 v0, v2, v1
	v_cvt_pk_bf16_f32 v0, v0, v113
	v_add_f32_e32 v2, v18, v1
	v_add_f32_e32 v16, v34, v1
	ds_write_b16 v196, v0
	v_cvt_pk_bf16_f32 v0, v2, v113
	v_add_f32_e32 v1, v50, v1
	ds_write_b16 v196, v0 offset:64
	v_cvt_pk_bf16_f32 v0, v16, v113
	ds_write_b16 v196, v0 offset:128
	v_cvt_pk_bf16_f32 v2, v1, v113
	v_mov_b32_e32 v16, v229
	ds_write_b16 v196, v2 offset:192
	v_lshl_add_u64 v[0:1], v[178:179], 0, s[38:39]
	s_waitcnt vmcnt(0)
	v_add_f32_e32 v2, v3, v16
	v_cvt_pk_bf16_f32 v2, v2, v113
	v_add_f32_e32 v3, v19, v16
	ds_write_b16 v197, v2
	v_cvt_pk_bf16_f32 v2, v3, v113
	v_add_f32_e32 v17, v35, v16
	ds_write_b16 v197, v2 offset:64
	v_cvt_pk_bf16_f32 v2, v17, v113
	v_add_f32_e32 v16, v51, v16
	ds_write_b16 v197, v2 offset:128
	v_cvt_pk_bf16_f32 v2, v16, v113
	v_mov_b32_e32 v3, v230
	ds_write_b16 v197, v2 offset:192
	s_waitcnt vmcnt(0)
	v_add_f32_e32 v2, v4, v3
	v_cvt_pk_bf16_f32 v2, v2, v113
	v_add_f32_e32 v4, v20, v3
	ds_write_b16 v198, v2
	v_cvt_pk_bf16_f32 v2, v4, v113
	v_add_f32_e32 v16, v36, v3
	v_add_f32_e32 v3, v52, v3
	ds_write_b16 v198, v2 offset:64
	v_cvt_pk_bf16_f32 v2, v16, v113
	ds_write_b16 v198, v2 offset:128
	v_cvt_pk_bf16_f32 v2, v3, v113
	v_mov_b32_e32 v3, v231
	ds_write_b16 v198, v2 offset:192
	s_waitcnt vmcnt(0)
	v_add_f32_e32 v2, v5, v3
	v_cvt_pk_bf16_f32 v2, v2, v113
	v_add_f32_e32 v4, v21, v3
	ds_write_b16 v199, v2
	v_cvt_pk_bf16_f32 v2, v4, v113
	v_add_f32_e32 v5, v37, v3
	v_add_f32_e32 v3, v53, v3
	ds_write_b16 v199, v2 offset:64
	v_cvt_pk_bf16_f32 v2, v5, v113
	ds_write_b16 v199, v2 offset:128
	v_cvt_pk_bf16_f32 v2, v3, v113
	v_mov_b32_e32 v3, v232
	ds_write_b16 v199, v2 offset:192
	s_waitcnt vmcnt(0)
	v_add_f32_e32 v2, v6, v3
	v_cvt_pk_bf16_f32 v2, v2, v113
	v_add_f32_e32 v4, v22, v3
	ds_write_b16 v200, v2
	v_cvt_pk_bf16_f32 v2, v4, v113
	v_add_f32_e32 v5, v38, v3
	v_add_f32_e32 v3, v54, v3
	ds_write_b16 v200, v2 offset:64
	v_cvt_pk_bf16_f32 v2, v5, v113
	ds_write_b16 v200, v2 offset:128
	v_cvt_pk_bf16_f32 v2, v3, v113
	v_mov_b32_e32 v3, v233
	ds_write_b16 v200, v2 offset:192
	v_lshl_add_u64 v[0:1], v[176:177], 0, s[38:39]
	s_waitcnt vmcnt(0)
	v_add_f32_e32 v2, v7, v3
	v_cvt_pk_bf16_f32 v2, v2, v113
	v_add_f32_e32 v4, v23, v3
	ds_write_b16 v201, v2
	v_cvt_pk_bf16_f32 v2, v4, v113
	v_add_f32_e32 v5, v39, v3
	v_add_f32_e32 v3, v55, v3
	ds_write_b16 v201, v2 offset:64
	v_cvt_pk_bf16_f32 v2, v5, v113
	ds_write_b16 v201, v2 offset:128
	v_cvt_pk_bf16_f32 v2, v3, v113
	v_mov_b32_e32 v3, v234
	ds_write_b16 v201, v2 offset:192
	s_waitcnt vmcnt(0)
	v_add_f32_e32 v2, v8, v3
	v_cvt_pk_bf16_f32 v2, v2, v113
	v_add_f32_e32 v4, v24, v3
	ds_write_b16 v202, v2
	v_cvt_pk_bf16_f32 v2, v4, v113
	v_add_f32_e32 v5, v40, v3
	v_add_f32_e32 v3, v56, v3
	ds_write_b16 v202, v2 offset:64
	v_cvt_pk_bf16_f32 v2, v5, v113
	ds_write_b16 v202, v2 offset:128
	v_cvt_pk_bf16_f32 v2, v3, v113
	v_mov_b32_e32 v3, v235
	ds_write_b16 v202, v2 offset:192
	s_waitcnt vmcnt(0)
	v_add_f32_e32 v2, v9, v3
	v_cvt_pk_bf16_f32 v2, v2, v113
	v_add_f32_e32 v4, v25, v3
	ds_write_b16 v203, v2
	v_cvt_pk_bf16_f32 v2, v4, v113
	v_add_f32_e32 v5, v41, v3
	v_add_f32_e32 v3, v57, v3
	ds_write_b16 v203, v2 offset:64
	v_cvt_pk_bf16_f32 v2, v5, v113
	ds_write_b16 v203, v2 offset:128
	v_cvt_pk_bf16_f32 v2, v3, v113
	v_mov_b32_e32 v3, v236
	ds_write_b16 v203, v2 offset:192
	s_waitcnt vmcnt(0)
	v_add_f32_e32 v2, v10, v3
	v_cvt_pk_bf16_f32 v2, v2, v113
	v_add_f32_e32 v4, v26, v3
	ds_write_b16 v204, v2
	v_cvt_pk_bf16_f32 v2, v4, v113
	v_add_f32_e32 v5, v42, v3
	v_add_f32_e32 v3, v58, v3
	ds_write_b16 v204, v2 offset:64
	v_cvt_pk_bf16_f32 v2, v5, v113
	ds_write_b16 v204, v2 offset:128
	v_cvt_pk_bf16_f32 v2, v3, v113
	v_mov_b32_e32 v3, v237
	ds_write_b16 v204, v2 offset:192
	v_lshl_add_u64 v[0:1], v[174:175], 0, s[38:39]
	s_waitcnt vmcnt(0)
; __device__ __forceinline__ int crow(int r, int hi) { return (r & 3) + 8 * (r >> 2) + 4 * hi; }
; __device__ __forceinline__ unsigned pk2(float lo, float hi) { return pg8::cvt_pk_bf16(lo, hi); }
; __device__ __forceinline__ float bflo(unsigned w) { return __uint_as_float(w << 16); }
; __device__ __forceinline__ float bfhi(unsigned w) { return __uint_as_float(w & 0xffff0000u); }
; __device__ __forceinline__ void sgu_unit(const Args& a, int l, int unit, unsigned char* ldsg) {
;     ...
;         for (int r = 0; r < 16; ++r) { const int i = iw * 32 + att::crow(r, hi); const float bias = a.in[7][(l * 8 + g) * 128 + i];
; #pragma unroll
;             for (int d0 = 0; d0 < 4; ++d0) *(bf16r*)(lds + OT_OFF + i * OT_PITCH + (eh * 128 + d0 * 32 + r32) * 2) = (bf16r)(pk2(o[d0][r] + bias, 0.f) & 0xffffu); }
;         __syncthreads();
; #pragma unroll
;         for (int k = 0; k < 8; ++k) { const int c = tid + 512 * k, row = c >> 5, cc = c & 31; const size_t gro = (size_t)(row0 + row);
;             const v4u uu = *(const v4u*)(UA + gro * DA + g * 256 + cc * 8), gg = *(const v4u*)(GA + gro * DA + g * 256 + cc * 8), oo = *(const v4u*)(lds + OT_OFF + row * OT_PITCH + cc * 16);
;             v4u w;
;             w.x = pk2(bflo(oo.x) * bflo(uu.x) * bflo(gg.x), bfhi(oo.x) * bfhi(uu.x) * bfhi(gg.x));
;             w.y = pk2(bflo(oo.y) * bflo(uu.y) * bflo(gg.y), bfhi(oo.y) * bfhi(uu.y) * bfhi(gg.y));
;             w.z = pk2(bflo(oo.z) * bflo(uu.z) * bflo(gg.z), bfhi(oo.z) * bfhi(uu.z) * bfhi(gg.z));
;             w.w = pk2(bflo(oo.w) * bflo(uu.w) * bflo(gg.w), bfhi(oo.w) * bfhi(uu.w) * bfhi(gg.w));
;             *(v4u*)(Y + gro * DM + g * 256 + cc * 8) = w; }
	v_add_f32_e32 v2, v11, v3
	v_cvt_pk_bf16_f32 v2, v2, v113
	v_add_f32_e32 v4, v27, v3
	ds_write_b16 v205, v2
	v_cvt_pk_bf16_f32 v2, v4, v113
	v_add_f32_e32 v5, v43, v3
	v_add_f32_e32 v3, v59, v3
	ds_write_b16 v205, v2 offset:64
	v_cvt_pk_bf16_f32 v2, v5, v113
	ds_write_b16 v205, v2 offset:128
	v_cvt_pk_bf16_f32 v2, v3, v113
	v_mov_b32_e32 v3, v238
	ds_write_b16 v205, v2 offset:192
	s_waitcnt vmcnt(0)
	v_add_f32_e32 v2, v12, v3
	v_cvt_pk_bf16_f32 v2, v2, v113
	v_add_f32_e32 v4, v28, v3
	ds_write_b16 v206, v2
	v_cvt_pk_bf16_f32 v2, v4, v113
	v_add_f32_e32 v5, v44, v3
	v_add_f32_e32 v3, v60, v3
	ds_write_b16 v206, v2 offset:64
	v_cvt_pk_bf16_f32 v2, v5, v113
	ds_write_b16 v206, v2 offset:128
	v_cvt_pk_bf16_f32 v2, v3, v113
	v_mov_b32_e32 v3, v239
	ds_write_b16 v206, v2 offset:192
	s_waitcnt vmcnt(0)
	v_add_f32_e32 v2, v13, v3
	v_cvt_pk_bf16_f32 v2, v2, v113
	v_add_f32_e32 v4, v29, v3
	ds_write_b16 v207, v2
	v_cvt_pk_bf16_f32 v2, v4, v113
	v_add_f32_e32 v5, v45, v3
	v_add_f32_e32 v3, v61, v3
	ds_write_b16 v207, v2 offset:64
	v_cvt_pk_bf16_f32 v2, v5, v113
	ds_write_b16 v207, v2 offset:128
	v_cvt_pk_bf16_f32 v2, v3, v113
	v_mov_b32_e32 v3, v240
	ds_write_b16 v207, v2 offset:192
	v_lshl_add_u64 v[12:13], v[130:131], 0, s[38:39]
	s_waitcnt vmcnt(0)
	v_add_f32_e32 v2, v14, v3
	v_cvt_pk_bf16_f32 v2, v2, v113
	v_add_f32_e32 v4, v30, v3
	ds_write_b16 v208, v2
	v_cvt_pk_bf16_f32 v2, v4, v113
	v_add_f32_e32 v5, v46, v3
	v_add_f32_e32 v3, v62, v3
	ds_write_b16 v208, v2 offset:64
	v_cvt_pk_bf16_f32 v2, v5, v113
	ds_write_b16 v208, v2 offset:128
	v_cvt_pk_bf16_f32 v6, v3, v113
	v_mov_b32_e32 v7, v241
	v_lshl_add_u64 v[0:1], v[114:115], 0, s[38:39]
	v_add_co_u32_e32 v2, vcc, s53, v0
	ds_write_b16 v208, v6 offset:192
	s_nop 0
	v_addc_co_u32_e32 v3, vcc, 0, v1, vcc
	v_add_co_u32_e32 v4, vcc, s54, v0
	s_waitcnt vmcnt(0)
	v_add_f32_e32 v0, v15, v7
	v_cvt_pk_bf16_f32 v0, v0, v113
	v_addc_co_u32_e32 v5, vcc, 0, v1, vcc
	v_add_f32_e32 v1, v31, v7
	ds_write_b16 v209, v0
	v_cvt_pk_bf16_f32 v0, v1, v113
	v_add_f32_e32 v6, v47, v7
	ds_write_b16 v209, v0 offset:64
	v_cvt_pk_bf16_f32 v0, v6, v113
	v_add_f32_e32 v7, v63, v7
	ds_write_b16 v209, v0 offset:128
	v_cvt_pk_bf16_f32 v0, v7, v113
	ds_write_b16 v209, v0 offset:192
	s_waitcnt lgkmcnt(0)
	s_barrier
	v_lshl_add_u64 v[30:31], v[114:115], 0, s[38:39]
	v_add_co_u32_e32 v254, vcc, s53, v30
	s_nop 1
	v_addc_co_u32_e32 v255, vcc, 0, v31, vcc
	global_load_dwordx4 v[32:35], v[254:255], off
	s_nop 0
	v_add_co_u32_e32 v254, vcc, s54, v30
	s_nop 1
	v_addc_co_u32_e32 v255, vcc, 0, v31, vcc
	global_load_dwordx4 v[226:229], v[254:255], off
	s_nop 0
	v_lshl_add_u64 v[30:31], v[116:117], 0, s[38:39]
	v_add_co_u32_e32 v254, vcc, s53, v30
	s_nop 1
	v_addc_co_u32_e32 v255, vcc, 0, v31, vcc
	global_load_dwordx4 v[36:39], v[254:255], off
	s_nop 0
	v_add_co_u32_e32 v254, vcc, s54, v30
	s_nop 1
	v_addc_co_u32_e32 v255, vcc, 0, v31, vcc
	global_load_dwordx4 v[230:233], v[254:255], off
	s_nop 0
	v_lshl_add_u64 v[30:31], v[118:119], 0, s[38:39]
	v_add_co_u32_e32 v254, vcc, s53, v30
	s_nop 1
	v_addc_co_u32_e32 v255, vcc, 0, v31, vcc
	global_load_dwordx4 v[40:43], v[254:255], off
	s_nop 0
	v_add_co_u32_e32 v254, vcc, s54, v30
	s_nop 1
	v_addc_co_u32_e32 v255, vcc, 0, v31, vcc
	global_load_dwordx4 v[234:237], v[254:255], off
	s_nop 0
	v_lshl_add_u64 v[30:31], v[120:121], 0, s[38:39]
	v_add_co_u32_e32 v254, vcc, s53, v30
	s_nop 1
	v_addc_co_u32_e32 v255, vcc, 0, v31, vcc
	global_load_dwordx4 v[44:47], v[254:255], off
	s_nop 0
	v_add_co_u32_e32 v254, vcc, s54, v30
	s_nop 1
	v_addc_co_u32_e32 v255, vcc, 0, v31, vcc
	global_load_dwordx4 v[238:241], v[254:255], off
	s_nop 0
	v_lshl_add_u64 v[30:31], v[122:123], 0, s[38:39]
	v_add_co_u32_e32 v254, vcc, s53, v30
	s_nop 1
	v_addc_co_u32_e32 v255, vcc, 0, v31, vcc
	global_load_dwordx4 v[48:51], v[254:255], off
	s_nop 0
	v_add_co_u32_e32 v254, vcc, s54, v30
	s_nop 1
	v_addc_co_u32_e32 v255, vcc, 0, v31, vcc
	global_load_dwordx4 v[242:245], v[254:255], off
	s_nop 0
	v_lshl_add_u64 v[30:31], v[124:125], 0, s[38:39]
	v_add_co_u32_e32 v254, vcc, s53, v30
	s_nop 1
	v_addc_co_u32_e32 v255, vcc, 0, v31, vcc
	global_load_dwordx4 v[52:55], v[254:255], off
	s_nop 0
	v_add_co_u32_e32 v254, vcc, s54, v30
	s_nop 1
	v_addc_co_u32_e32 v255, vcc, 0, v31, vcc
	global_load_dwordx4 v[246:249], v[254:255], off
	s_nop 0
	v_lshl_add_u64 v[30:31], v[126:127], 0, s[38:39]
	v_add_co_u32_e32 v254, vcc, s53, v30
	s_nop 1
	v_addc_co_u32_e32 v255, vcc, 0, v31, vcc
	global_load_dwordx4 v[56:59], v[254:255], off
	s_nop 0
	v_add_co_u32_e32 v254, vcc, s54, v30
	s_nop 1
	v_addc_co_u32_e32 v255, vcc, 0, v31, vcc
	global_load_dwordx4 v[250:253], v[254:255], off
	s_nop 0
	v_lshl_add_u64 v[30:31], v[128:129], 0, s[38:39]
	v_add_co_u32_e32 v254, vcc, s53, v30
	s_nop 1
	v_addc_co_u32_e32 v255, vcc, 0, v31, vcc
	global_load_dwordx4 v[60:63], v[254:255], off
	s_nop 0
	v_add_co_u32_e32 v254, vcc, s54, v30
	s_nop 1
	v_addc_co_u32_e32 v255, vcc, 0, v31, vcc
	global_load_dwordx4 v[64:67], v[254:255], off
	s_nop 0
	s_nop 0
	ds_read_b128 v[8:11], v210
	v_lshl_add_u64 v[14:15], v[116:117], 0, s[38:39]
	v_add_co_u32_e32 v16, vcc, s53, v14
	s_waitcnt lgkmcnt(0)
	v_lshlrev_b32_e32 v18, 16, v8
	v_and_b32_e32 v8, 0xffff0000, v8
	v_lshlrev_b32_e32 v19, 16, v9
	v_and_b32_e32 v9, 0xffff0000, v9
	v_lshlrev_b32_e32 v20, 16, v10
	v_and_b32_e32 v10, 0xffff0000, v10
	v_lshlrev_b32_e32 v21, 16, v11
	v_and_b32_e32 v11, 0xffff0000, v11
	v_addc_co_u32_e32 v17, vcc, 0, v15, vcc
	v_add_co_u32_e32 v14, vcc, s54, v14
	s_waitcnt vmcnt(14)
; __device__ __forceinline__ unsigned pk2(float lo, float hi) { return pg8::cvt_pk_bf16(lo, hi); }
; __device__ __forceinline__ float bflo(unsigned w) { return __uint_as_float(w << 16); }
; __device__ __forceinline__ float bfhi(unsigned w) { return __uint_as_float(w & 0xffff0000u); }
; __device__ __forceinline__ void sgu_unit(const Args& a, int l, int unit, unsigned char* ldsg) {
;     ...
;         for (int k = 0; k < 8; ++k) { const int c = tid + 512 * k, row = c >> 5, cc = c & 31; const size_t gro = (size_t)(row0 + row);
;             const v4u uu = *(const v4u*)(UA + gro * DA + g * 256 + cc * 8), gg = *(const v4u*)(GA + gro * DA + g * 256 + cc * 8), oo = *(const v4u*)(lds + OT_OFF + row * OT_PITCH + cc * 16);
;             v4u w;
;             w.x = pk2(bflo(oo.x) * bflo(uu.x) * bflo(gg.x), bfhi(oo.x) * bfhi(uu.x) * bfhi(gg.x));
;             w.y = pk2(bflo(oo.y) * bflo(uu.y) * bflo(gg.y), bfhi(oo.y) * bfhi(uu.y) * bfhi(gg.y));
;             w.z = pk2(bflo(oo.z) * bflo(uu.z) * bflo(gg.z), bfhi(oo.z) * bfhi(uu.z) * bfhi(gg.z));
;             w.w = pk2(bflo(oo.w) * bflo(uu.w) * bflo(gg.w), bfhi(oo.w) * bfhi(uu.w) * bfhi(gg.w));
;             *(v4u*)(Y + gro * DM + g * 256 + cc * 8) = w; }
	v_mov_b32_e32 v0, v32
	v_mov_b32_e32 v1, v33
	v_mov_b32_e32 v2, v34
	v_mov_b32_e32 v3, v35
	v_mov_b32_e32 v4, v226
	v_mov_b32_e32 v5, v227
	v_mov_b32_e32 v6, v228
	v_mov_b32_e32 v7, v229
	v_lshlrev_b32_e32 v22, 16, v0
	v_and_b32_e32 v0, 0xffff0000, v0
	v_lshlrev_b32_e32 v24, 16, v1
	v_and_b32_e32 v1, 0xffff0000, v1
	v_lshlrev_b32_e32 v26, 16, v2
	v_and_b32_e32 v2, 0xffff0000, v2
	v_lshlrev_b32_e32 v28, 16, v3
	v_and_b32_e32 v3, 0xffff0000, v3
	v_lshlrev_b32_e32 v23, 16, v4
	v_and_b32_e32 v4, 0xffff0000, v4
	v_lshlrev_b32_e32 v25, 16, v5
	v_and_b32_e32 v5, 0xffff0000, v5
	v_lshlrev_b32_e32 v27, 16, v6
	v_and_b32_e32 v6, 0xffff0000, v6
	v_lshlrev_b32_e32 v29, 16, v7
	v_and_b32_e32 v7, 0xffff0000, v7
	v_mul_f32_e32 v0, v8, v0
	v_mul_f32_e32 v1, v9, v1
	v_mul_f32_e32 v2, v10, v2
	v_mul_f32_e32 v3, v11, v3
	v_mul_f32_e32 v18, v18, v22
	v_mul_f32_e32 v8, v19, v24
	v_mul_f32_e32 v9, v20, v26
	v_mul_f32_e32 v10, v21, v28
	v_mul_f32_e32 v0, v0, v4
	v_mul_f32_e32 v1, v1, v5
	v_mul_f32_e32 v2, v2, v6
	v_mul_f32_e32 v3, v3, v7
	v_mul_f32_e32 v11, v18, v23
	v_mul_f32_e32 v4, v8, v25
	v_mul_f32_e32 v5, v9, v27
	v_mul_f32_e32 v6, v10, v29
	v_cvt_pk_bf16_f32 v0, v11, v0
	v_cvt_pk_bf16_f32 v1, v4, v1
	v_cvt_pk_bf16_f32 v2, v5, v2
	v_cvt_pk_bf16_f32 v3, v6, v3
	global_store_dwordx4 v[12:13], v[0:3], off
	v_addc_co_u32_e32 v15, vcc, 0, v15, vcc
	ds_read_b128 v[8:11], v211
	v_lshl_add_u64 v[14:15], v[118:119], 0, s[38:39]
	v_add_co_u32_e32 v16, vcc, s53, v14
	v_lshl_add_u64 v[12:13], v[132:133], 0, s[38:39]
	s_waitcnt lgkmcnt(0)
	v_lshlrev_b32_e32 v18, 16, v8
	v_and_b32_e32 v8, 0xffff0000, v8
	v_lshlrev_b32_e32 v19, 16, v9
	v_and_b32_e32 v9, 0xffff0000, v9
	v_lshlrev_b32_e32 v20, 16, v10
	v_and_b32_e32 v10, 0xffff0000, v10
	v_lshlrev_b32_e32 v21, 16, v11
	v_and_b32_e32 v11, 0xffff0000, v11
	v_addc_co_u32_e32 v17, vcc, 0, v15, vcc
	v_add_co_u32_e32 v14, vcc, s54, v14
	s_waitcnt vmcnt(13)
	v_mov_b32_e32 v0, v36
	v_mov_b32_e32 v1, v37
	v_mov_b32_e32 v2, v38
	v_mov_b32_e32 v3, v39
	v_mov_b32_e32 v4, v230
	v_mov_b32_e32 v5, v231
	v_mov_b32_e32 v6, v232
	v_mov_b32_e32 v7, v233
	v_lshlrev_b32_e32 v22, 16, v0
	v_and_b32_e32 v0, 0xffff0000, v0
	v_lshlrev_b32_e32 v24, 16, v1
	v_and_b32_e32 v1, 0xffff0000, v1
	v_lshlrev_b32_e32 v26, 16, v2
	v_and_b32_e32 v2, 0xffff0000, v2
	v_lshlrev_b32_e32 v28, 16, v3
	v_and_b32_e32 v3, 0xffff0000, v3
	v_lshlrev_b32_e32 v23, 16, v4
	v_and_b32_e32 v4, 0xffff0000, v4
	v_lshlrev_b32_e32 v25, 16, v5
	v_and_b32_e32 v5, 0xffff0000, v5
	v_lshlrev_b32_e32 v27, 16, v6
	v_and_b32_e32 v6, 0xffff0000, v6
	v_lshlrev_b32_e32 v29, 16, v7
	v_and_b32_e32 v7, 0xffff0000, v7
	v_mul_f32_e32 v0, v8, v0
	v_mul_f32_e32 v1, v9, v1
	v_mul_f32_e32 v2, v10, v2
	v_mul_f32_e32 v3, v11, v3
	v_mul_f32_e32 v18, v18, v22
	v_mul_f32_e32 v8, v19, v24
	v_mul_f32_e32 v9, v20, v26
	v_mul_f32_e32 v10, v21, v28
	v_mul_f32_e32 v0, v0, v4
	v_mul_f32_e32 v1, v1, v5
	v_mul_f32_e32 v2, v2, v6
	v_mul_f32_e32 v3, v3, v7
	v_mul_f32_e32 v11, v18, v23
	v_mul_f32_e32 v4, v8, v25
	v_mul_f32_e32 v5, v9, v27
	v_mul_f32_e32 v6, v10, v29
	v_cvt_pk_bf16_f32 v0, v11, v0
	v_cvt_pk_bf16_f32 v1, v4, v1
	v_cvt_pk_bf16_f32 v2, v5, v2
	v_cvt_pk_bf16_f32 v3, v6, v3
	global_store_dwordx4 v[12:13], v[0:3], off
	v_addc_co_u32_e32 v15, vcc, 0, v15, vcc
	ds_read_b128 v[8:11], v212
	v_lshl_add_u64 v[14:15], v[120:121], 0, s[38:39]
	v_add_co_u32_e32 v16, vcc, s53, v14
	v_lshl_add_u64 v[12:13], v[134:135], 0, s[38:39]
	s_waitcnt lgkmcnt(0)
	v_lshlrev_b32_e32 v18, 16, v8
	v_and_b32_e32 v8, 0xffff0000, v8
	v_lshlrev_b32_e32 v19, 16, v9
	v_and_b32_e32 v9, 0xffff0000, v9
	v_lshlrev_b32_e32 v20, 16, v10
	v_and_b32_e32 v10, 0xffff0000, v10
	v_lshlrev_b32_e32 v21, 16, v11
	v_and_b32_e32 v11, 0xffff0000, v11
	v_addc_co_u32_e32 v17, vcc, 0, v15, vcc
	v_add_co_u32_e32 v14, vcc, s54, v14
	s_waitcnt vmcnt(12)
	v_mov_b32_e32 v0, v40
	v_mov_b32_e32 v1, v41
	v_mov_b32_e32 v2, v42
	v_mov_b32_e32 v3, v43
	v_mov_b32_e32 v4, v234
	v_mov_b32_e32 v5, v235
	v_mov_b32_e32 v6, v236
	v_mov_b32_e32 v7, v237
	v_lshlrev_b32_e32 v22, 16, v0
	v_and_b32_e32 v0, 0xffff0000, v0
	v_lshlrev_b32_e32 v24, 16, v1
	v_and_b32_e32 v1, 0xffff0000, v1
	v_lshlrev_b32_e32 v26, 16, v2
	v_and_b32_e32 v2, 0xffff0000, v2
	v_lshlrev_b32_e32 v28, 16, v3
	v_and_b32_e32 v3, 0xffff0000, v3
	v_lshlrev_b32_e32 v23, 16, v4
	v_and_b32_e32 v4, 0xffff0000, v4
	v_lshlrev_b32_e32 v25, 16, v5
	v_and_b32_e32 v5, 0xffff0000, v5
	v_lshlrev_b32_e32 v27, 16, v6
	v_and_b32_e32 v6, 0xffff0000, v6
	v_lshlrev_b32_e32 v29, 16, v7
	v_and_b32_e32 v7, 0xffff0000, v7
	v_mul_f32_e32 v0, v8, v0
	v_mul_f32_e32 v1, v9, v1
	v_mul_f32_e32 v2, v10, v2
	v_mul_f32_e32 v3, v11, v3
	v_mul_f32_e32 v18, v18, v22
	v_mul_f32_e32 v8, v19, v24
	v_mul_f32_e32 v9, v20, v26
	v_mul_f32_e32 v10, v21, v28
	v_mul_f32_e32 v0, v0, v4
	v_mul_f32_e32 v1, v1, v5
	v_mul_f32_e32 v2, v2, v6
	v_mul_f32_e32 v3, v3, v7
	v_mul_f32_e32 v11, v18, v23
	v_mul_f32_e32 v4, v8, v25
	v_mul_f32_e32 v5, v9, v27
	v_mul_f32_e32 v6, v10, v29
	v_cvt_pk_bf16_f32 v0, v11, v0
	v_cvt_pk_bf16_f32 v1, v4, v1
	v_cvt_pk_bf16_f32 v2, v5, v2
	v_cvt_pk_bf16_f32 v3, v6, v3
	global_store_dwordx4 v[12:13], v[0:3], off
	v_addc_co_u32_e32 v15, vcc, 0, v15, vcc
	ds_read_b128 v[8:11], v213
	v_lshl_add_u64 v[14:15], v[122:123], 0, s[38:39]
	v_add_co_u32_e32 v16, vcc, s53, v14
	v_lshl_add_u64 v[12:13], v[136:137], 0, s[38:39]
	s_waitcnt lgkmcnt(0)
	v_lshlrev_b32_e32 v18, 16, v8
	v_and_b32_e32 v8, 0xffff0000, v8
	v_lshlrev_b32_e32 v19, 16, v9
	v_and_b32_e32 v9, 0xffff0000, v9
	v_lshlrev_b32_e32 v20, 16, v10
	v_and_b32_e32 v10, 0xffff0000, v10
	v_lshlrev_b32_e32 v21, 16, v11
	v_and_b32_e32 v11, 0xffff0000, v11
	v_addc_co_u32_e32 v17, vcc, 0, v15, vcc
	v_add_co_u32_e32 v14, vcc, s54, v14
	s_waitcnt vmcnt(11)
; __device__ __forceinline__ unsigned pk2(float lo, float hi) { return pg8::cvt_pk_bf16(lo, hi); }
; __device__ __forceinline__ float bflo(unsigned w) { return __uint_as_float(w << 16); }
; __device__ __forceinline__ float bfhi(unsigned w) { return __uint_as_float(w & 0xffff0000u); }
; __device__ __forceinline__ void sgu_unit(const Args& a, int l, int unit, unsigned char* ldsg) {
;     ...
;         for (int k = 0; k < 8; ++k) { const int c = tid + 512 * k, row = c >> 5, cc = c & 31; const size_t gro = (size_t)(row0 + row);
;             const v4u uu = *(const v4u*)(UA + gro * DA + g * 256 + cc * 8), gg = *(const v4u*)(GA + gro * DA + g * 256 + cc * 8), oo = *(const v4u*)(lds + OT_OFF + row * OT_PITCH + cc * 16);
;             v4u w;
;             w.x = pk2(bflo(oo.x) * bflo(uu.x) * bflo(gg.x), bfhi(oo.x) * bfhi(uu.x) * bfhi(gg.x));
;             w.y = pk2(bflo(oo.y) * bflo(uu.y) * bflo(gg.y), bfhi(oo.y) * bfhi(uu.y) * bfhi(gg.y));
;             w.z = pk2(bflo(oo.z) * bflo(uu.z) * bflo(gg.z), bfhi(oo.z) * bfhi(uu.z) * bfhi(gg.z));
;             w.w = pk2(bflo(oo.w) * bflo(uu.w) * bflo(gg.w), bfhi(oo.w) * bfhi(uu.w) * bfhi(gg.w));
;             *(v4u*)(Y + gro * DM + g * 256 + cc * 8) = w; }
	v_mov_b32_e32 v0, v44
	v_mov_b32_e32 v1, v45
	v_mov_b32_e32 v2, v46
	v_mov_b32_e32 v3, v47
	v_mov_b32_e32 v4, v238
	v_mov_b32_e32 v5, v239
	v_mov_b32_e32 v6, v240
	v_mov_b32_e32 v7, v241
	v_lshlrev_b32_e32 v22, 16, v0
	v_and_b32_e32 v0, 0xffff0000, v0
	v_lshlrev_b32_e32 v24, 16, v1
	v_and_b32_e32 v1, 0xffff0000, v1
	v_lshlrev_b32_e32 v26, 16, v2
	v_and_b32_e32 v2, 0xffff0000, v2
	v_lshlrev_b32_e32 v28, 16, v3
	v_and_b32_e32 v3, 0xffff0000, v3
	v_lshlrev_b32_e32 v23, 16, v4
	v_and_b32_e32 v4, 0xffff0000, v4
	v_lshlrev_b32_e32 v25, 16, v5
	v_and_b32_e32 v5, 0xffff0000, v5
	v_lshlrev_b32_e32 v27, 16, v6
	v_and_b32_e32 v6, 0xffff0000, v6
	v_lshlrev_b32_e32 v29, 16, v7
	v_and_b32_e32 v7, 0xffff0000, v7
	v_mul_f32_e32 v0, v8, v0
	v_mul_f32_e32 v1, v9, v1
	v_mul_f32_e32 v2, v10, v2
	v_mul_f32_e32 v3, v11, v3
	v_mul_f32_e32 v18, v18, v22
	v_mul_f32_e32 v8, v19, v24
	v_mul_f32_e32 v9, v20, v26
	v_mul_f32_e32 v10, v21, v28
	v_mul_f32_e32 v0, v0, v4
	v_mul_f32_e32 v1, v1, v5
	v_mul_f32_e32 v2, v2, v6
	v_mul_f32_e32 v3, v3, v7
	v_mul_f32_e32 v11, v18, v23
	v_mul_f32_e32 v4, v8, v25
	v_mul_f32_e32 v5, v9, v27
	v_mul_f32_e32 v6, v10, v29
	v_cvt_pk_bf16_f32 v0, v11, v0
	v_cvt_pk_bf16_f32 v1, v4, v1
	v_cvt_pk_bf16_f32 v2, v5, v2
	v_cvt_pk_bf16_f32 v3, v6, v3
	global_store_dwordx4 v[12:13], v[0:3], off
	v_addc_co_u32_e32 v15, vcc, 0, v15, vcc
	ds_read_b128 v[8:11], v214
	v_lshl_add_u64 v[14:15], v[124:125], 0, s[38:39]
	v_add_co_u32_e32 v16, vcc, s53, v14
	v_lshl_add_u64 v[12:13], v[138:139], 0, s[38:39]
	s_waitcnt lgkmcnt(0)
	v_lshlrev_b32_e32 v18, 16, v8
	v_and_b32_e32 v8, 0xffff0000, v8
	v_lshlrev_b32_e32 v19, 16, v9
	v_and_b32_e32 v9, 0xffff0000, v9
	v_lshlrev_b32_e32 v20, 16, v10
	v_and_b32_e32 v10, 0xffff0000, v10
	v_lshlrev_b32_e32 v21, 16, v11
	v_and_b32_e32 v11, 0xffff0000, v11
	v_addc_co_u32_e32 v17, vcc, 0, v15, vcc
	v_add_co_u32_e32 v14, vcc, s54, v14
	s_waitcnt vmcnt(10)
	v_mov_b32_e32 v0, v48
	v_mov_b32_e32 v1, v49
	v_mov_b32_e32 v2, v50
	v_mov_b32_e32 v3, v51
	v_mov_b32_e32 v4, v242
	v_mov_b32_e32 v5, v243
	v_mov_b32_e32 v6, v244
	v_mov_b32_e32 v7, v245
	v_lshlrev_b32_e32 v22, 16, v0
	v_and_b32_e32 v0, 0xffff0000, v0
	v_lshlrev_b32_e32 v24, 16, v1
	v_and_b32_e32 v1, 0xffff0000, v1
	v_lshlrev_b32_e32 v26, 16, v2
	v_and_b32_e32 v2, 0xffff0000, v2
	v_lshlrev_b32_e32 v28, 16, v3
	v_and_b32_e32 v3, 0xffff0000, v3
	v_lshlrev_b32_e32 v23, 16, v4
	v_and_b32_e32 v4, 0xffff0000, v4
	v_lshlrev_b32_e32 v25, 16, v5
	v_and_b32_e32 v5, 0xffff0000, v5
	v_lshlrev_b32_e32 v27, 16, v6
	v_and_b32_e32 v6, 0xffff0000, v6
	v_lshlrev_b32_e32 v29, 16, v7
	v_and_b32_e32 v7, 0xffff0000, v7
	v_mul_f32_e32 v0, v8, v0
	v_mul_f32_e32 v1, v9, v1
	v_mul_f32_e32 v2, v10, v2
	v_mul_f32_e32 v3, v11, v3
	v_mul_f32_e32 v18, v18, v22
	v_mul_f32_e32 v8, v19, v24
	v_mul_f32_e32 v9, v20, v26
	v_mul_f32_e32 v10, v21, v28
	v_mul_f32_e32 v0, v0, v4
	v_mul_f32_e32 v1, v1, v5
	v_mul_f32_e32 v2, v2, v6
	v_mul_f32_e32 v3, v3, v7
	v_mul_f32_e32 v11, v18, v23
	v_mul_f32_e32 v4, v8, v25
	v_mul_f32_e32 v5, v9, v27
	v_mul_f32_e32 v6, v10, v29
	v_cvt_pk_bf16_f32 v0, v11, v0
	v_cvt_pk_bf16_f32 v1, v4, v1
	v_cvt_pk_bf16_f32 v2, v5, v2
	v_cvt_pk_bf16_f32 v3, v6, v3
	global_store_dwordx4 v[12:13], v[0:3], off
	v_addc_co_u32_e32 v15, vcc, 0, v15, vcc
	ds_read_b128 v[8:11], v215
	v_lshl_add_u64 v[14:15], v[126:127], 0, s[38:39]
	v_add_co_u32_e32 v16, vcc, s53, v14
	v_lshl_add_u64 v[12:13], v[140:141], 0, s[38:39]
	s_waitcnt lgkmcnt(0)
	v_lshlrev_b32_e32 v18, 16, v8
	v_and_b32_e32 v8, 0xffff0000, v8
	v_lshlrev_b32_e32 v19, 16, v9
	v_and_b32_e32 v9, 0xffff0000, v9
	v_lshlrev_b32_e32 v20, 16, v10
	v_and_b32_e32 v10, 0xffff0000, v10
	v_lshlrev_b32_e32 v21, 16, v11
	v_and_b32_e32 v11, 0xffff0000, v11
	v_addc_co_u32_e32 v17, vcc, 0, v15, vcc
	v_add_co_u32_e32 v14, vcc, s54, v14
	s_waitcnt vmcnt(9)
; __device__ __forceinline__ unsigned pk2(float lo, float hi) { return pg8::cvt_pk_bf16(lo, hi); }
; __device__ __forceinline__ float bflo(unsigned w) { return __uint_as_float(w << 16); }
; __device__ __forceinline__ float bfhi(unsigned w) { return __uint_as_float(w & 0xffff0000u); }
; __device__ __forceinline__ void sgu_unit(const Args& a, int l, int unit, unsigned char* ldsg) {
;     ...
;         for (int k = 0; k < 8; ++k) { const int c = tid + 512 * k, row = c >> 5, cc = c & 31; const size_t gro = (size_t)(row0 + row);
;             const v4u uu = *(const v4u*)(UA + gro * DA + g * 256 + cc * 8), gg = *(const v4u*)(GA + gro * DA + g * 256 + cc * 8), oo = *(const v4u*)(lds + OT_OFF + row * OT_PITCH + cc * 16);
;             v4u w;
;             w.x = pk2(bflo(oo.x) * bflo(uu.x) * bflo(gg.x), bfhi(oo.x) * bfhi(uu.x) * bfhi(gg.x));
;             w.y = pk2(bflo(oo.y) * bflo(uu.y) * bflo(gg.y), bfhi(oo.y) * bfhi(uu.y) * bfhi(gg.y));
;             w.z = pk2(bflo(oo.z) * bflo(uu.z) * bflo(gg.z), bfhi(oo.z) * bfhi(uu.z) * bfhi(gg.z));
;             w.w = pk2(bflo(oo.w) * bflo(uu.w) * bflo(gg.w), bfhi(oo.w) * bfhi(uu.w) * bfhi(gg.w));
;             *(v4u*)(Y + gro * DM + g * 256 + cc * 8) = w; }
	v_mov_b32_e32 v0, v52
	v_mov_b32_e32 v1, v53
	v_mov_b32_e32 v2, v54
	v_mov_b32_e32 v3, v55
	v_mov_b32_e32 v4, v246
	v_mov_b32_e32 v5, v247
	v_mov_b32_e32 v6, v248
	v_mov_b32_e32 v7, v249
	v_lshlrev_b32_e32 v22, 16, v0
	v_and_b32_e32 v0, 0xffff0000, v0
	v_lshlrev_b32_e32 v24, 16, v1
	v_and_b32_e32 v1, 0xffff0000, v1
	v_lshlrev_b32_e32 v26, 16, v2
	v_and_b32_e32 v2, 0xffff0000, v2
	v_lshlrev_b32_e32 v28, 16, v3
	v_and_b32_e32 v3, 0xffff0000, v3
	v_lshlrev_b32_e32 v23, 16, v4
	v_and_b32_e32 v4, 0xffff0000, v4
	v_lshlrev_b32_e32 v25, 16, v5
	v_and_b32_e32 v5, 0xffff0000, v5
	v_lshlrev_b32_e32 v27, 16, v6
	v_and_b32_e32 v6, 0xffff0000, v6
	v_lshlrev_b32_e32 v29, 16, v7
	v_and_b32_e32 v7, 0xffff0000, v7
	v_mul_f32_e32 v0, v8, v0
	v_mul_f32_e32 v1, v9, v1
	v_mul_f32_e32 v2, v10, v2
	v_mul_f32_e32 v3, v11, v3
	v_mul_f32_e32 v18, v18, v22
	v_mul_f32_e32 v8, v19, v24
	v_mul_f32_e32 v9, v20, v26
	v_mul_f32_e32 v10, v21, v28
	v_mul_f32_e32 v0, v0, v4
	v_mul_f32_e32 v1, v1, v5
	v_mul_f32_e32 v2, v2, v6
	v_mul_f32_e32 v3, v3, v7
	v_mul_f32_e32 v11, v18, v23
	v_mul_f32_e32 v4, v8, v25
	v_mul_f32_e32 v5, v9, v27
	v_mul_f32_e32 v6, v10, v29
	v_cvt_pk_bf16_f32 v0, v11, v0
	v_cvt_pk_bf16_f32 v1, v4, v1
	v_cvt_pk_bf16_f32 v2, v5, v2
	v_cvt_pk_bf16_f32 v3, v6, v3
	global_store_dwordx4 v[12:13], v[0:3], off
	v_addc_co_u32_e32 v15, vcc, 0, v15, vcc
	ds_read_b128 v[8:11], v216
	v_lshl_add_u64 v[14:15], v[128:129], 0, s[38:39]
	v_add_co_u32_e32 v16, vcc, s53, v14
	v_lshl_add_u64 v[12:13], v[142:143], 0, s[38:39]
	s_waitcnt lgkmcnt(0)
	v_lshlrev_b32_e32 v18, 16, v8
	v_and_b32_e32 v8, 0xffff0000, v8
	v_lshlrev_b32_e32 v19, 16, v9
	v_and_b32_e32 v9, 0xffff0000, v9
	v_lshlrev_b32_e32 v20, 16, v10
	v_and_b32_e32 v10, 0xffff0000, v10
	v_lshlrev_b32_e32 v21, 16, v11
	v_and_b32_e32 v11, 0xffff0000, v11
	v_addc_co_u32_e32 v17, vcc, 0, v15, vcc
	v_add_co_u32_e32 v14, vcc, s54, v14
	s_waitcnt vmcnt(8)
	v_mov_b32_e32 v0, v56
	v_mov_b32_e32 v1, v57
	v_mov_b32_e32 v2, v58
	v_mov_b32_e32 v3, v59
	v_mov_b32_e32 v4, v250
	v_mov_b32_e32 v5, v251
	v_mov_b32_e32 v6, v252
	v_mov_b32_e32 v7, v253
	v_lshlrev_b32_e32 v22, 16, v0
	v_and_b32_e32 v0, 0xffff0000, v0
	v_lshlrev_b32_e32 v24, 16, v1
	v_and_b32_e32 v1, 0xffff0000, v1
	v_lshlrev_b32_e32 v26, 16, v2
	v_and_b32_e32 v2, 0xffff0000, v2
	v_lshlrev_b32_e32 v28, 16, v3
	v_and_b32_e32 v3, 0xffff0000, v3
	v_lshlrev_b32_e32 v23, 16, v4
	v_and_b32_e32 v4, 0xffff0000, v4
	v_lshlrev_b32_e32 v25, 16, v5
	v_and_b32_e32 v5, 0xffff0000, v5
	v_lshlrev_b32_e32 v27, 16, v6
	v_and_b32_e32 v6, 0xffff0000, v6
	v_lshlrev_b32_e32 v29, 16, v7
	v_and_b32_e32 v7, 0xffff0000, v7
	v_mul_f32_e32 v0, v8, v0
	v_mul_f32_e32 v1, v9, v1
	v_mul_f32_e32 v2, v10, v2
	v_mul_f32_e32 v3, v11, v3
	v_mul_f32_e32 v18, v18, v22
	v_mul_f32_e32 v8, v19, v24
	v_mul_f32_e32 v9, v20, v26
	v_mul_f32_e32 v10, v21, v28
	v_mul_f32_e32 v0, v0, v4
	v_mul_f32_e32 v1, v1, v5
	v_mul_f32_e32 v2, v2, v6
	v_mul_f32_e32 v3, v3, v7
	v_mul_f32_e32 v11, v18, v23
	v_mul_f32_e32 v4, v8, v25
	v_mul_f32_e32 v5, v9, v27
	v_mul_f32_e32 v6, v10, v29
	v_cvt_pk_bf16_f32 v0, v11, v0
	v_cvt_pk_bf16_f32 v1, v4, v1
	v_cvt_pk_bf16_f32 v2, v5, v2
	v_cvt_pk_bf16_f32 v3, v6, v3
	global_store_dwordx4 v[12:13], v[0:3], off
	v_addc_co_u32_e32 v15, vcc, 0, v15, vcc
	ds_read_b128 v[8:11], v217
	v_lshl_add_u64 v[12:13], v[144:145], 0, s[38:39]
	s_add_u32 s38, s38, 0x200
	s_addc_u32 s39, s39, 0
	s_add_u32 s26, s26, 0x400
	s_waitcnt lgkmcnt(0)
	v_lshlrev_b32_e32 v14, 16, v8
	v_and_b32_e32 v8, 0xffff0000, v8
	v_lshlrev_b32_e32 v15, 16, v9
	v_and_b32_e32 v9, 0xffff0000, v9
	v_lshlrev_b32_e32 v16, 16, v10
	v_and_b32_e32 v10, 0xffff0000, v10
	v_lshlrev_b32_e32 v17, 16, v11
	v_and_b32_e32 v11, 0xffff0000, v11
	s_addc_u32 s27, s27, 0
	s_cmpk_lg_i32 s38, 0x800
	s_waitcnt vmcnt(7)
	v_mov_b32_e32 v0, v60
	v_mov_b32_e32 v1, v61
	v_mov_b32_e32 v2, v62
	v_mov_b32_e32 v3, v63
	v_mov_b32_e32 v4, v64
	v_mov_b32_e32 v5, v65
	v_mov_b32_e32 v6, v66
	v_mov_b32_e32 v7, v67
	v_lshlrev_b32_e32 v18, 16, v0
	v_and_b32_e32 v0, 0xffff0000, v0
	v_lshlrev_b32_e32 v20, 16, v1
	v_and_b32_e32 v1, 0xffff0000, v1
	v_lshlrev_b32_e32 v22, 16, v2
	v_and_b32_e32 v2, 0xffff0000, v2
	v_lshlrev_b32_e32 v24, 16, v3
	v_and_b32_e32 v3, 0xffff0000, v3
	v_lshlrev_b32_e32 v19, 16, v4
	v_and_b32_e32 v4, 0xffff0000, v4
	v_lshlrev_b32_e32 v21, 16, v5
	v_and_b32_e32 v5, 0xffff0000, v5
	v_lshlrev_b32_e32 v23, 16, v6
	v_and_b32_e32 v6, 0xffff0000, v6
	v_lshlrev_b32_e32 v25, 16, v7
	v_and_b32_e32 v7, 0xffff0000, v7
	v_mul_f32_e32 v0, v8, v0
	v_mul_f32_e32 v1, v9, v1
	v_mul_f32_e32 v2, v10, v2
	v_mul_f32_e32 v3, v11, v3
	v_mul_f32_e32 v14, v14, v18
	v_mul_f32_e32 v8, v15, v20
	v_mul_f32_e32 v9, v16, v22
	v_mul_f32_e32 v10, v17, v24
	v_mul_f32_e32 v0, v0, v4
	v_mul_f32_e32 v1, v1, v5
	v_mul_f32_e32 v2, v2, v6
	v_mul_f32_e32 v3, v3, v7
	v_mul_f32_e32 v11, v14, v19
	v_mul_f32_e32 v4, v8, v21
	v_mul_f32_e32 v5, v9, v23
	v_mul_f32_e32 v6, v10, v25
	v_cvt_pk_bf16_f32 v0, v11, v0
	v_cvt_pk_bf16_f32 v1, v4, v1
	v_cvt_pk_bf16_f32 v2, v5, v2
	v_cvt_pk_bf16_f32 v3, v6, v3
	global_store_dwordx4 v[12:13], v[0:3], off
	s_cbranch_scc0 .LBB0_931

; __global__ void __launch_bounds__(NWAVES * 64, 2) mega_fwd(Args a) {
	.amdhsa_kernel _Z8mega_fwd4Args
		.amdhsa_group_segment_fixed_size 0
		.amdhsa_private_segment_fixed_size 0
		.amdhsa_kernarg_size 472
		.amdhsa_user_sgpr_count 2
		.amdhsa_user_sgpr_dispatch_ptr 0
		.amdhsa_user_sgpr_queue_ptr 0
		.amdhsa_user_sgpr_kernarg_segment_ptr 1
		.amdhsa_user_sgpr_dispatch_id 0
		.amdhsa_user_sgpr_kernarg_preload_length 0
		.amdhsa_user_sgpr_kernarg_preload_offset 0
		.amdhsa_user_sgpr_private_segment_size 0
		.amdhsa_uses_dynamic_stack 0
		.amdhsa_enable_private_segment 0
		.amdhsa_system_sgpr_workgroup_id_x 1
		.amdhsa_system_sgpr_workgroup_id_y 0
		.amdhsa_system_sgpr_workgroup_id_z 0
		.amdhsa_system_sgpr_workgroup_info 0
		.amdhsa_system_vgpr_workitem_id 2
		.amdhsa_next_free_vgpr 256
		.amdhsa_next_free_sgpr 98
		.amdhsa_accum_offset 256
		.amdhsa_reserve_vcc 1
		.amdhsa_float_round_mode_32 0
		.amdhsa_float_round_mode_16_64 0
		.amdhsa_float_denorm_mode_32 3
		.amdhsa_float_denorm_mode_16_64 3
		.amdhsa_dx10_clamp 1
		.amdhsa_ieee_mode 1
		.amdhsa_fp16_overflow 0
		.amdhsa_tg_split 0
		.amdhsa_exception_fp_ieee_invalid_op 0
		.amdhsa_exception_fp_denorm_src 0
		.amdhsa_exception_fp_ieee_div_zero 0
		.amdhsa_exception_fp_ieee_overflow 0
		.amdhsa_exception_fp_ieee_underflow 0
		.amdhsa_exception_fp_ieee_inexact 0
		.amdhsa_exception_int_div_zero 0
	.end_amdhsa_kernel

; __global__ void __launch_bounds__(NWAVES * 64, 2) mega_fwd(Args a) {
amdhsa.kernels:
  - .agpr_count:     0
    .args:
      - .offset:         0
        .size:           216
        .value_kind:     by_value
      - .offset:         216
        .size:           4
        .value_kind:     hidden_block_count_x
      - .offset:         220
        .size:           4
        .value_kind:     hidden_block_count_y
      - .offset:         224
        .size:           4
        .value_kind:     hidden_block_count_z
      - .offset:         228
        .size:           2
        .value_kind:     hidden_group_size_x
      - .offset:         230
        .size:           2
        .value_kind:     hidden_group_size_y
      - .offset:         232
        .size:           2
        .value_kind:     hidden_group_size_z
      - .offset:         234
        .size:           2
        .value_kind:     hidden_remainder_x
      - .offset:         236
        .size:           2
        .value_kind:     hidden_remainder_y
      - .offset:         238
        .size:           2
        .value_kind:     hidden_remainder_z
      - .offset:         256
        .size:           8
        .value_kind:     hidden_global_offset_x
      - .offset:         264
        .size:           8
        .value_kind:     hidden_global_offset_y
      - .offset:         272
        .size:           8
        .value_kind:     hidden_global_offset_z
      - .offset:         280
        .size:           2
        .value_kind:     hidden_grid_dims
      - .offset:         304
        .size:           8
        .value_kind:     hidden_multigrid_sync_arg
      - .offset:         336
        .size:           4
        .value_kind:     hidden_dynamic_lds_size
    .group_segment_fixed_size: 0
    .kernarg_segment_align: 8
    .kernarg_segment_size: 472
    .language:       OpenCL C
    .language_version:
      - 2
      - 0
    .max_flat_workgroup_size: 512
    .name:           _Z8mega_fwd4Args
    .private_segment_fixed_size: 0
    .sgpr_count:     104
    .sgpr_spill_count: 0
    .symbol:         _Z8mega_fwd4Args.kd
    .uniform_work_group_size: 1
    .uses_dynamic_stack: false
    .vgpr_count:     256
    .vgpr_spill_count: 0
    .wavefront_size: 64
